# MLA loop unrolled by 2 (LDS buffer parity as immediate offsets), saddr global prefetch with running scalar pointers, LDS reads issued right behind the MFMAs that free the ring slot
# speedup vs baseline: 1.0630x; 1.0243x over previous
; #define LAS __attribute__((address_space(3)))
; #define GAS __attribute__((address_space(1)))
; __device__ __forceinline__ void attn_unit(const bf16_t* Qh, const bf16_t* Kh, const bf16_t* Vh, bf16_t* Oh  , int S, int qb, LAS unsigned char* lds, int tid) {
;     const int lane = tid & 63, r32 = lane & 31, hi = lane >> 5; const int wid = __builtin_amdgcn_readfirstlane(tid >> 6);
;     const int qrow = qb * 512 + wid * 64 + r32;
;     const bf16_t* Qw = Qh + (size_t)qrow * 96 + 8 * hi;
;     LAS unsigned char* ql = lds + QOFF + wid * 12288 + lane * 16;
; #pragma unroll
;     for (int s = 0; s < 6; ++s) { *(LAS bf16x8*)(ql + s * 1024) = GLD(bf16x8, Qw + 16 * s); *(LAS bf16x8*)(ql + (6 + s) * 1024) = GLD(bf16x8, Qw + 32 * 96 + 16 * s); }
;     const bool has1 = tid < 256; const int kc0 = tid, kc1 = has1 ? tid + 512 : tid;
;     const unsigned kd0 = (unsigned)((kc0 / 12) * KPITCH + (kc0 % 12) * 16);
;     const unsigned kd1 = has1 ? (unsigned)((kc1 / 12) * KPITCH + (kc1 % 12) * 16) : (unsigned)(DUMMY + (tid - 256) * 16);
;     const unsigned kd1n = has1 ? BUF : 0u;
;     const unsigned vd = (unsigned)(KBYTES + ((tid & 7) >> 2) * 4096 + (tid >> 3) * 64 + (tid & 3) * 16);
;     const GAS u32x4* Kg = (const GAS u32x4*)Kh; const GAS u32x4* Vg = (const GAS u32x4*)Vh;
;     const int NT = S >> 6;
;     u32x4 ka = GLD(u32x4, Kg + kc0), kb = GLD(u32x4, Kg + kc1), va = GLD(u32x4, Vg + tid);
;     *(LAS u32x4*)(lds + kd0) = ka; *(LAS u32x4*)(lds + kd1) = kb; *(LAS u32x4*)(lds + vd) = va;
;     __syncthreads();
;     f32x16 oa0 = {}, oa1 = {}, ob0 = {}, ob1 = {}; float ma = 0.f, la = 0.f, mb = 0.f, lb = 0.f;
;     const unsigned kfo = (unsigned)(r32 * KPITCH + hi * 16);
.LBB0_76:
	s_abs_i32 s1, s24
	s_mul_hi_u32 s4, s1, s19
	s_mul_i32 s16, s4, s13
	s_sub_i32 s1, s1, s16
	s_ashr_i32 s0, s24, 31
	s_add_i32 s16, s4, 1
	s_sub_i32 s17, s1, s13
	s_cmp_ge_u32 s1, s13
	s_cselect_b32 s4, s16, s4
	s_cselect_b32 s1, s17, s1
	s_add_i32 s16, s4, 1
	s_cmp_ge_u32 s1, s13
	s_cselect_b32 s1, s16, s4
	s_xor_b32 s1, s1, s0
	s_sub_i32 s0, s1, s0
	s_mul_i32 s1, s0, s13
	s_sub_i32 s4, s24, s1
	s_ashr_i32 s1, s0, 31
	s_lshl_b64 s[26:27], s[0:1], s82
	s_mul_i32 s1, s27, 0xc0
	s_mul_hi_u32 s16, s26, 0xc0
	s_add_i32 s1, s16, s1
	s_mul_i32 s16, s26, 0xc0
	s_add_u32 s40, s96, s16
	s_addc_u32 s41, s97, s1
	s_add_u32 s16, s84, s16
	s_addc_u32 s17, s85, s1
	s_lshl_b64 s[26:27], s[26:27], 7
	s_add_u32 s26, s86, s26
	v_readfirstlane_b32 s1, v172
	s_addc_u32 s27, s87, s27
	s_lshl_b32 s4, s4, 9
	s_and_b32 s25, s1, 0xffffffc0
	s_add_i32 s4, s4, s25
	v_or_b32_e32 v136, s4, v148
	v_mov_b64_e32 v[0:1], s[40:41]
	v_mad_i64_i32 v[0:1], s[40:41], v136, s75, v[0:1]
	v_lshl_add_u64 v[40:41], v[0:1], 0, v[168:169]
	v_add_co_u32_e32 v44, vcc, s33, v40
	v_lshlrev_b64 v[60:61], 4, v[172:173]
	s_nop 0
	v_addc_co_u32_e32 v45, vcc, 0, v41, vcc
	v_lshl_add_u64 v[48:49], s[16:17], 0, v[60:61]
	global_load_dwordx4 v[0:3], v[40:41], off
	global_load_dwordx4 v[4:7], v[40:41], off offset:32
	global_load_dwordx4 v[8:11], v[40:41], off offset:64
	global_load_dwordx4 v[12:15], v[44:45], off offset:2080
	global_load_dwordx4 v[16:19], v[44:45], off offset:2112
	global_load_dwordx4 v[20:23], v[40:41], off offset:96
	global_load_dwordx4 v[24:27], v[40:41], off offset:128
	global_load_dwordx4 v[28:31], v[44:45], off offset:2144
	global_load_dwordx4 v[32:35], v[44:45], off offset:2176
	global_load_dwordx4 v[36:39], v[44:45], off offset:2048
	s_nop 0
	global_load_dwordx4 v[40:43], v[40:41], off offset:160
	s_nop 0
	global_load_dwordx4 v[44:47], v[44:45], off offset:2208
	s_nop 0
	global_load_dwordx4 v[48:51], v[48:49], off
	v_lshlrev_b64 v[62:63], 4, v[132:133]
	v_lshl_add_u64 v[52:53], s[16:17], 0, v[62:63]
	global_load_dwordx4 v[52:55], v[52:53], off
	v_lshl_add_u64 v[138:139], s[26:27], 0, v[60:61]
	global_load_dwordx4 v[56:59], v[138:139], off
	s_lshr_b32 s1, s1, 6
	s_mulk_i32 s1, 0x3000
	v_add_u32_e32 v135, s1, v149
	v_add_u32_e32 v163, 0, v150
	v_add_u32_e32 v162, 0, v157
	s_add_u32 s26, s16, 0x3000
	s_movk_i32 s1, 0x2000
	s_addc_u32 s27, s17, 0
	v_ashrrev_i32_e32 v137, 31, v136
	s_waitcnt vmcnt(0)
	ds_write_b128 v135, v[0:3] offset:43008
	s_waitcnt vmcnt(13)
	ds_write_b128 v135, v[4:7] offset:44032
	s_waitcnt vmcnt(12)
	ds_write_b128 v135, v[8:11] offset:45056
	s_waitcnt vmcnt(9)
	ds_write_b128 v135, v[20:23] offset:46080
	s_waitcnt vmcnt(8)
	ds_write_b128 v135, v[24:27] offset:47104
	s_waitcnt vmcnt(5)
	ds_write_b128 v135, v[36:39] offset:49152
	ds_write_b128 v135, v[12:15] offset:50176
	ds_write_b128 v135, v[16:19] offset:51200
	ds_write_b128 v135, v[28:31] offset:52224
	ds_write_b128 v135, v[32:35] offset:53248
	s_waitcnt vmcnt(4)
	ds_write_b128 v135, v[40:43] offset:48128
	s_waitcnt vmcnt(3)
	ds_write_b128 v135, v[44:47] offset:54272
	s_waitcnt vmcnt(2)
	ds_write_b128 v163, v[48:51]
	s_waitcnt vmcnt(1)
	ds_write_b128 v156, v[52:55]
	s_waitcnt vmcnt(0)
	ds_write_b128 v162, v[56:59] offset:13312
	s_waitcnt lgkmcnt(0)
	s_barrier
	v_mov_b64_e32 v[0:1], 0
	v_mov_b64_e32 v[2:3], 0
	v_mov_b64_e32 v[4:5], 0
	v_mov_b64_e32 v[6:7], 0
	v_mov_b64_e32 v[8:9], 0
	v_mov_b64_e32 v[10:11], 0
	v_mov_b64_e32 v[12:13], 0
	v_mov_b64_e32 v[14:15], 0
	v_mov_b64_e32 v[16:17], 0
	v_mov_b64_e32 v[18:19], 0
	v_mov_b64_e32 v[20:21], 0
	v_mov_b64_e32 v[22:23], 0
	v_mov_b64_e32 v[24:25], 0
	v_mov_b64_e32 v[26:27], 0
	v_mov_b64_e32 v[28:29], 0
	v_mov_b64_e32 v[30:31], 0
	v_mov_b64_e32 v[32:33], 0
	v_mov_b64_e32 v[34:35], 0
	v_mov_b64_e32 v[36:37], 0
	v_mov_b64_e32 v[38:39], 0
	v_mov_b64_e32 v[40:41], 0
	v_mov_b64_e32 v[42:43], 0
	v_mov_b64_e32 v[44:45], 0
	v_mov_b64_e32 v[46:47], 0
	v_mov_b64_e32 v[48:49], 0
	v_mov_b64_e32 v[50:51], 0
	v_mov_b64_e32 v[52:53], 0
	v_mov_b64_e32 v[54:55], 0
	v_mov_b64_e32 v[56:57], 0
	v_mov_b64_e32 v[58:59], 0
	v_mov_b64_e32 v[60:61], 0
	v_mov_b64_e32 v[62:63], 0
	v_mov_b32_e32 v140, 0
	v_mov_b32_e32 v141, 0
	v_lshlrev_b32_e32 v171, 4, v172
	v_lshlrev_b32_e32 v184, 4, v132
	v_lshlrev_b32_e32 v146, 4, v174
	v_readfirstlane_b32 s100, v138
	v_readfirstlane_b32 s101, v139
	s_add_u32 s26, s16, 0x3000
	s_addc_u32 s27, s17, 0
	s_mov_b32 s1, 1
	v_readfirstlane_b32 s4, v172
	s_nop 3
	s_cmp_ge_u32 s4, 0x100
	s_nop 0
	s_nop 0
; #define LAS __attribute__((address_space(3)))
; __device__ __forceinline__ void attn_unit(const bf16_t* Qh, const bf16_t* Kh, const bf16_t* Vh, bf16_t* Oh  , int S, int qb, LAS unsigned char* lds, int tid) {
;     ...
;     for (int t = 0; t < NT; ++t) {
;         const unsigned cur = (unsigned)(t & 1) * BUF, nxt = BUF - cur;
;         const int tn = t + 1 < NT ? t + 1 : t;
;         ka = GLD(u32x4, Kg + (size_t)tn * 768 + kc0); kb = GLD(u32x4, Kg + (size_t)tn * 768 + kc1); va = GLD(u32x4, Vg + (size_t)tn * 512 + tid);
;         u32x4 pf[4];
;         {
;             f32x16 p0 = {}, p1 = {};
; #pragma unroll
;             for (int s = 0; s < 6; ++s) {
;                 const bf16x8 a0 = *(const LAS bf16x8*)(lds + cur + kfo + s * 32), a1 = *(const LAS bf16x8*)(lds + cur + kfo + 32 * KPITCH + s * 32);
;                 const bf16x8 q = *(const LAS bf16x8*)(ql + s * 1024);
;                 p0 = __builtin_amdgcn_mfma_f32_32x32x16_bf16(a0, q, p0, 0, 0, 0); p1 = __builtin_amdgcn_mfma_f32_32x32x16_bf16(a1, q, p1, 0, 0, 0);
;             }
;             softmax_blk(p0, p1, oa0, oa1, ma, la, pf, t == 0);
.Lmla_prio:
	s_add_u32 s100, s100, 0x2000
	s_addc_u32 s101, s101, 0
	ds_read_b128 v[128:131], v155
	ds_read_b128 v[142:145], v155 offset:6656
	ds_read_b128 v[162:165], v135 offset:43008
	ds_read_b128 v[176:179], v155 offset:32
	ds_read_b128 v[180:183], v155 offset:6688
	ds_read_b128 v[186:189], v135 offset:44032
	s_waitcnt lgkmcnt(3)
	v_mfma_f32_32x32x16_bf16 v[64:79], v[128:131], v[162:165], 0
	v_mfma_f32_32x32x16_bf16 v[80:95], v[142:145], v[162:165], 0
	ds_read_b128 v[128:131], v155 offset:64
	ds_read_b128 v[142:145], v155 offset:6720
	ds_read_b128 v[162:165], v135 offset:45056
	global_load_dwordx4 v[218:221], v171, s[26:27]
	global_load_dwordx4 v[222:225], v184, s[26:27]
	s_add_u32 s26, s26, 0x3000
	s_addc_u32 s27, s27, 0
	s_waitcnt lgkmcnt(3)
	v_mfma_f32_32x32x16_bf16 v[64:79], v[176:179], v[186:189], v[64:79]
	v_mfma_f32_32x32x16_bf16 v[80:95], v[180:183], v[186:189], v[80:95]
	ds_read_b128 v[176:179], v155 offset:96
	ds_read_b128 v[180:183], v155 offset:6752
	ds_read_b128 v[186:189], v135 offset:46080
	s_waitcnt lgkmcnt(3)
	v_mfma_f32_32x32x16_bf16 v[64:79], v[128:131], v[162:165], v[64:79]
	v_mfma_f32_32x32x16_bf16 v[80:95], v[142:145], v[162:165], v[80:95]
	ds_read_b128 v[128:131], v155 offset:128
	ds_read_b128 v[142:145], v155 offset:6784
	ds_read_b128 v[162:165], v135 offset:47104
	s_waitcnt lgkmcnt(3)
	v_mfma_f32_32x32x16_bf16 v[64:79], v[176:179], v[186:189], v[64:79]
	v_mfma_f32_32x32x16_bf16 v[80:95], v[180:183], v[186:189], v[80:95]
	ds_read_b128 v[176:179], v155 offset:160
	ds_read_b128 v[180:183], v155 offset:6816
	ds_read_b128 v[186:189], v135 offset:48128
	s_waitcnt lgkmcnt(3)
	v_mfma_f32_32x32x16_bf16 v[64:79], v[128:131], v[162:165], v[64:79]
	v_mfma_f32_32x32x16_bf16 v[80:95], v[142:145], v[162:165], v[80:95]
	ds_read_b128 v[128:131], v155
	ds_read_b128 v[142:145], v155 offset:6656
	ds_read_b128 v[162:165], v135 offset:49152
	s_waitcnt lgkmcnt(3)
	v_mfma_f32_32x32x16_bf16 v[64:79], v[176:179], v[186:189], v[64:79]
	v_mfma_f32_32x32x16_bf16 v[80:95], v[180:183], v[186:189], v[80:95]
	ds_read_b128 v[176:179], v155 offset:32
	ds_read_b128 v[180:183], v155 offset:6688
	ds_read_b128 v[186:189], v135 offset:50176
	s_waitcnt lgkmcnt(3)
	v_mfma_f32_32x32x16_bf16 v[96:111], v[128:131], v[162:165], 0
	v_mfma_f32_32x32x16_bf16 v[112:127], v[142:145], v[162:165], 0
	ds_read_b128 v[128:131], v155 offset:64
	ds_read_b128 v[142:145], v155 offset:6720
	ds_read_b128 v[162:165], v135 offset:51200
	s_nop 5
	v_max3_f32 v248, v64, v65, v66
	v_max3_f32 v249, v80, v81, v82
	v_max3_f32 v248, v248, v67, v68
	v_max3_f32 v249, v249, v83, v84
	v_max3_f32 v248, v248, v69, v70
	v_max3_f32 v249, v249, v85, v86
	v_max3_f32 v248, v248, v71, v72
	v_max3_f32 v249, v249, v87, v88
	v_max3_f32 v248, v248, v73, v74
	v_max3_f32 v249, v249, v89, v90
	v_max3_f32 v248, v248, v75, v76
	v_max3_f32 v249, v249, v91, v92
	v_max3_f32 v248, v248, v77, v78
	v_max3_f32 v249, v249, v93, v94
	v_max3_f32 v248, v248, v79, v95
	v_max_f32_e32 v248, v248, v249
	v_mov_b32_e32 v251, v248
	s_nop 1
	v_permlane32_swap_b32_e32 v248, v251
	v_max_f32_e32 v167, v248, v251
	v_sub_f32_e32 v64, v64, v167
	v_sub_f32_e32 v65, v65, v167
	v_sub_f32_e32 v66, v66, v167
	v_sub_f32_e32 v67, v67, v167
	v_sub_f32_e32 v68, v68, v167
	v_sub_f32_e32 v69, v69, v167
	v_sub_f32_e32 v70, v70, v167
	v_sub_f32_e32 v71, v71, v167
	v_sub_f32_e32 v72, v72, v167
	s_waitcnt lgkmcnt(3)
	v_mfma_f32_32x32x16_bf16 v[96:111], v[176:179], v[186:189], v[96:111]
	v_mfma_f32_32x32x16_bf16 v[112:127], v[180:183], v[186:189], v[112:127]
	ds_read_b128 v[176:179], v155 offset:96
	ds_read_b128 v[180:183], v155 offset:6752
	ds_read_b128 v[186:189], v135 offset:52224
	v_sub_f32_e32 v73, v73, v167
	v_sub_f32_e32 v74, v74, v167
	v_sub_f32_e32 v75, v75, v167
	v_sub_f32_e32 v76, v76, v167
	v_sub_f32_e32 v77, v77, v167
	v_sub_f32_e32 v78, v78, v167
	v_sub_f32_e32 v79, v79, v167
	v_sub_f32_e32 v80, v80, v167
	v_sub_f32_e32 v81, v81, v167
	v_sub_f32_e32 v82, v82, v167
	v_sub_f32_e32 v83, v83, v167
	v_sub_f32_e32 v84, v84, v167
	v_sub_f32_e32 v85, v85, v167
	v_sub_f32_e32 v86, v86, v167
	v_sub_f32_e32 v87, v87, v167
	v_sub_f32_e32 v88, v88, v167
	v_sub_f32_e32 v89, v89, v167
	v_sub_f32_e32 v90, v90, v167
	v_sub_f32_e32 v91, v91, v167
	v_sub_f32_e32 v92, v92, v167
	v_sub_f32_e32 v93, v93, v167
	v_sub_f32_e32 v94, v94, v167
	v_sub_f32_e32 v95, v95, v167
	v_sub_f32_e32 v232, 0, v167
	v_sub_f32_e32 v233, 0, v167
	v_sub_f32_e32 v234, 0, v167
	v_sub_f32_e32 v235, 0, v167
	v_sub_f32_e32 v236, 0, v167
	s_waitcnt lgkmcnt(3)
	v_mfma_f32_32x32x16_bf16 v[96:111], v[128:131], v[162:165], v[96:111]
	v_mfma_f32_32x32x16_bf16 v[112:127], v[142:145], v[162:165], v[112:127]
	ds_read_b128 v[128:131], v155 offset:128
	ds_read_b128 v[142:145], v155 offset:6784
	ds_read_b128 v[162:165], v135 offset:53248
	v_sub_f32_e32 v237, 0, v167
	v_sub_f32_e32 v238, 0, v167
	v_sub_f32_e32 v239, 0, v167
	v_sub_f32_e32 v240, 0, v167
	v_sub_f32_e32 v241, 0, v167
	v_sub_f32_e32 v242, 0, v167
	v_sub_f32_e32 v243, 0, v167
	v_sub_f32_e32 v244, 0, v167
	v_sub_f32_e32 v245, 0, v167
	v_sub_f32_e32 v246, 0, v167
	v_sub_f32_e32 v247, 0, v167
	v_max3_f32 v248, v64, v65, v66
	v_max3_f32 v249, v80, v81, v82
	v_max3_f32 v248, v248, v67, v68
	v_max3_f32 v249, v249, v83, v84
	v_max3_f32 v248, v248, v69, v70
	v_max3_f32 v249, v249, v85, v86
	v_max3_f32 v248, v248, v71, v72
	v_max3_f32 v249, v249, v87, v88
	v_max3_f32 v248, v248, v73, v74
	v_max3_f32 v249, v249, v89, v90
	v_max3_f32 v248, v248, v75, v76
	v_max3_f32 v249, v249, v91, v92
	v_max3_f32 v248, v248, v77, v78
	v_max3_f32 v249, v249, v93, v94
	v_max3_f32 v248, v248, v79, v95
	v_max_f32_e32 v248, v248, v249
	v_mov_b32_e32 v251, v248
	s_waitcnt lgkmcnt(3)
	v_mfma_f32_32x32x16_bf16 v[96:111], v[176:179], v[186:189], v[96:111]
	v_mfma_f32_32x32x16_bf16 v[112:127], v[180:183], v[186:189], v[112:127]
	ds_read_b128 v[176:179], v155 offset:160
	ds_read_b128 v[180:183], v155 offset:6816
	ds_read_b128 v[186:189], v135 offset:54272
	s_nop 1
	v_permlane32_swap_b32_e32 v248, v251
	v_max_f32_e32 v167, v248, v251
	v_cmp_lt_f32_e32 vcc, s72, v167
	s_cbranch_vccnz .Lmla_rescAp
; #define LAS __attribute__((address_space(3)))
; #define MLA_PACK(P, b) (u32x4){cvt_pk_bf16(P[b], P[b + 1]), cvt_pk_bf16(P[b + 2], P[b + 3]), cvt_pk_bf16(P[b + 4], P[b + 5]), cvt_pk_bf16(P[b + 6], P[b + 7])}
; __device__ __forceinline__ void softmax_blk(f32x16& p0, f32x16& p1, f32x16& o0, f32x16& o1, float& mhat, float& lrun, u32x4 (&pf)[4], bool first) {
;     ...
;     float s0 = 0.f, s1 = 0.f;
; #pragma unroll
;     for (int e = 0; e < 16; ++e) { p0[e] = __builtin_amdgcn_exp2f(p0[e] - mhat); p1[e] = __builtin_amdgcn_exp2f(p1[e] - mhat); s0 += p0[e]; s1 += p1[e]; }
;     lrun += s0 + s1;
;     pf[0] = MLA_PACK(p0, 0); pf[1] = MLA_PACK(p0, 8); pf[2] = MLA_PACK(p1, 0); pf[3] = MLA_PACK(p1, 8);
; }
; __device__ __forceinline__ void attn_unit(const bf16_t* Qh, const bf16_t* Kh, const bf16_t* Vh, bf16_t* Oh  , int S, int qb, LAS unsigned char* lds, int tid) {
;     ...
;         *(LAS u32x4*)(lds + nxt + kd0) = ka; *(LAS u32x4*)(lds + (has1 ? nxt : 0u) + kd1) = kb; *(LAS u32x4*)(lds + nxt + vd) = va;
;         __syncthreads();
.Lmla_rescAp_back:
	v_exp_f32_e32 v64, v64
	v_exp_f32_e32 v65, v65
	v_exp_f32_e32 v66, v66
	v_exp_f32_e32 v67, v67
	v_exp_f32_e32 v68, v68
	v_exp_f32_e32 v69, v69
	v_exp_f32_e32 v70, v70
	v_exp_f32_e32 v71, v71
	v_add_f32_e32 v166, v64, v65
	v_add_f32_e32 v140, v140, v66
	v_add_f32_e32 v166, v166, v67
	v_cvt_pk_bf16_f32 v64, v64, v65
	v_cvt_pk_bf16_f32 v65, v66, v67
	v_exp_f32_e32 v72, v72
	v_exp_f32_e32 v73, v73
	v_exp_f32_e32 v74, v74
	v_exp_f32_e32 v75, v75
	v_add_f32_e32 v140, v140, v68
	v_add_f32_e32 v166, v166, v69
	v_add_f32_e32 v140, v140, v70
	v_add_f32_e32 v166, v166, v71
	v_cvt_pk_bf16_f32 v66, v68, v69
	v_cvt_pk_bf16_f32 v67, v70, v71
	v_exp_f32_e32 v76, v76
	s_waitcnt lgkmcnt(3)
	v_mfma_f32_32x32x16_bf16 v[96:111], v[128:131], v[162:165], v[96:111]
	v_mfma_f32_32x32x16_bf16 v[112:127], v[142:145], v[162:165], v[112:127]
	v_exp_f32_e32 v77, v77
	v_exp_f32_e32 v78, v78
	v_exp_f32_e32 v79, v79
	v_add_f32_e32 v140, v140, v72
	v_add_f32_e32 v166, v166, v73
	v_add_f32_e32 v140, v140, v74
	v_add_f32_e32 v166, v166, v75
	v_cvt_pk_bf16_f32 v68, v72, v73
	v_cvt_pk_bf16_f32 v69, v74, v75
	v_exp_f32_e32 v80, v80
	v_exp_f32_e32 v81, v81
	v_exp_f32_e32 v82, v82
	v_exp_f32_e32 v83, v83
	v_add_f32_e32 v140, v140, v76
	v_add_f32_e32 v166, v166, v77
	v_add_f32_e32 v140, v140, v78
	v_add_f32_e32 v166, v166, v79
	v_cvt_pk_bf16_f32 v70, v76, v77
	v_cvt_pk_bf16_f32 v71, v78, v79
	v_exp_f32_e32 v84, v84
	v_exp_f32_e32 v85, v85
	v_exp_f32_e32 v86, v86
	v_exp_f32_e32 v87, v87
	v_add_f32_e32 v140, v140, v80
	v_add_f32_e32 v166, v166, v81
	v_add_f32_e32 v140, v140, v82
	v_add_f32_e32 v166, v166, v83
	v_cvt_pk_bf16_f32 v72, v80, v81
	s_waitcnt lgkmcnt(0)
	v_mfma_f32_32x32x16_bf16 v[96:111], v[176:179], v[186:189], v[96:111]
	v_mfma_f32_32x32x16_bf16 v[112:127], v[180:183], v[186:189], v[112:127]
	v_cvt_pk_bf16_f32 v73, v82, v83
	v_exp_f32_e32 v88, v88
	v_exp_f32_e32 v89, v89
	v_exp_f32_e32 v90, v90
	v_exp_f32_e32 v91, v91
	v_add_f32_e32 v140, v140, v84
	v_add_f32_e32 v166, v166, v85
	v_add_f32_e32 v140, v140, v86
	v_add_f32_e32 v166, v166, v87
	v_cvt_pk_bf16_f32 v74, v84, v85
	v_cvt_pk_bf16_f32 v75, v86, v87
	v_exp_f32_e32 v92, v92
	v_exp_f32_e32 v93, v93
	v_exp_f32_e32 v94, v94
	v_exp_f32_e32 v95, v95
	v_add_f32_e32 v140, v140, v88
	v_add_f32_e32 v166, v166, v89
	v_add_f32_e32 v140, v140, v90
	v_add_f32_e32 v166, v166, v91
	v_cvt_pk_bf16_f32 v76, v88, v89
	v_cvt_pk_bf16_f32 v77, v90, v91
	v_add_f32_e32 v140, v140, v92
	v_add_f32_e32 v166, v166, v93
	v_add_f32_e32 v140, v140, v94
	v_add_f32_e32 v166, v166, v95
	v_cvt_pk_bf16_f32 v78, v92, v93
	v_cvt_pk_bf16_f32 v79, v94, v95
	v_add_f32_e32 v140, v140, v166
	s_nop 7
	s_nop 3
	v_max3_f32 v248, v96, v97, v98
	v_max3_f32 v249, v112, v113, v114
	v_max3_f32 v248, v248, v99, v100
	v_max3_f32 v249, v249, v115, v116
	v_max3_f32 v248, v248, v101, v102
	v_max3_f32 v249, v249, v117, v118
	v_max3_f32 v248, v248, v103, v104
	v_max3_f32 v249, v249, v119, v120
	v_max3_f32 v248, v248, v105, v106
	v_max3_f32 v249, v249, v121, v122
	v_max3_f32 v248, v248, v107, v108
	v_max3_f32 v249, v249, v123, v124
	v_max3_f32 v248, v248, v109, v110
	v_max3_f32 v249, v249, v125, v126
	v_max3_f32 v248, v248, v111, v127
	v_max_f32_e32 v248, v248, v249
	v_mov_b32_e32 v251, v248
	s_nop 1
	v_permlane32_swap_b32_e32 v248, v251
	v_max_f32_e32 v167, v248, v251
	v_sub_f32_e32 v96, v96, v167
	v_sub_f32_e32 v97, v97, v167
	v_sub_f32_e32 v98, v98, v167
	v_sub_f32_e32 v99, v99, v167
	v_sub_f32_e32 v100, v100, v167
	v_sub_f32_e32 v101, v101, v167
	v_sub_f32_e32 v102, v102, v167
	v_sub_f32_e32 v103, v103, v167
	v_sub_f32_e32 v104, v104, v167
	v_sub_f32_e32 v105, v105, v167
	v_sub_f32_e32 v106, v106, v167
	v_sub_f32_e32 v107, v107, v167
	v_sub_f32_e32 v108, v108, v167
	v_sub_f32_e32 v109, v109, v167
	v_sub_f32_e32 v110, v110, v167
	v_sub_f32_e32 v111, v111, v167
	v_sub_f32_e32 v112, v112, v167
	v_sub_f32_e32 v113, v113, v167
	v_sub_f32_e32 v114, v114, v167
	v_sub_f32_e32 v115, v115, v167
	v_sub_f32_e32 v116, v116, v167
	v_sub_f32_e32 v117, v117, v167
	v_sub_f32_e32 v118, v118, v167
	v_sub_f32_e32 v119, v119, v167
	v_sub_f32_e32 v120, v120, v167
	v_sub_f32_e32 v121, v121, v167
	v_sub_f32_e32 v122, v122, v167
	v_sub_f32_e32 v123, v123, v167
	v_sub_f32_e32 v124, v124, v167
	v_sub_f32_e32 v125, v125, v167
	v_sub_f32_e32 v126, v126, v167
	v_sub_f32_e32 v127, v127, v167
	v_sub_f32_e32 v190, 0, v167
	v_sub_f32_e32 v191, 0, v167
	v_sub_f32_e32 v192, 0, v167
	v_sub_f32_e32 v193, 0, v167
	v_sub_f32_e32 v194, 0, v167
	v_sub_f32_e32 v195, 0, v167
	v_sub_f32_e32 v196, 0, v167
	v_sub_f32_e32 v197, 0, v167
	v_sub_f32_e32 v198, 0, v167
	v_sub_f32_e32 v199, 0, v167
	v_sub_f32_e32 v200, 0, v167
	v_sub_f32_e32 v201, 0, v167
	v_sub_f32_e32 v202, 0, v167
	v_sub_f32_e32 v203, 0, v167
	v_sub_f32_e32 v204, 0, v167
	v_sub_f32_e32 v205, 0, v167
	s_waitcnt vmcnt(0)
	ds_write_b128 v150, v[218:221] offset:21504
	ds_write_b128 v159, v[222:225]
	s_waitcnt lgkmcnt(0)
	s_barrier
; #define LAS __attribute__((address_space(3)))
; __device__ __forceinline__ s16x4 vtr(LAS const unsigned char* p) { return __builtin_bit_cast(s16x4, __builtin_amdgcn_ds_read_tr16_b64_v4i16((LAS s16x4*)p)); }
; __device__ __forceinline__ void pv_blk(const u32x4 (&pf)[4], f32x16& o0, f32x16& o1, LAS const unsigned char* vbase) {
; #pragma unroll
;     for (int ks = 0; ks < 4; ++ks) {
;         const bf16x8 p = __builtin_bit_cast(bf16x8, pf[ks]);
;         { const s16x4 lo = vtr(vbase + ks * 1024), hh = vtr(vbase + ks * 1024 + 512); const bf16x8 vf = {lo[0], lo[1], lo[2], lo[3], hh[0], hh[1], hh[2], hh[3]};
;           o0 = __builtin_amdgcn_mfma_f32_32x32x16_bf16(vf, p, o0, 0, 0, 0); }
;         { const s16x4 lo = vtr(vbase + 4096 + ks * 1024), hh = vtr(vbase + 4096 + ks * 1024 + 512); const bf16x8 vf = {lo[0], lo[1], lo[2], lo[3], hh[0], hh[1], hh[2], hh[3]};
;           o1 = __builtin_amdgcn_mfma_f32_32x32x16_bf16(vf, p, o1, 0, 0, 0); }
;     }
; __device__ __forceinline__ void attn_unit(const bf16_t* Qh, const bf16_t* Kh, const bf16_t* Vh, bf16_t* Oh  , int S, int qb, LAS unsigned char* lds, int tid) {
;     ...
;     for (int t = 0; t < NT; ++t) {
;         const unsigned cur = (unsigned)(t & 1) * BUF, nxt = BUF - cur;
;         const int tn = t + 1 < NT ? t + 1 : t;
;         ka = GLD(u32x4, Kg + (size_t)tn * 768 + kc0); kb = GLD(u32x4, Kg + (size_t)tn * 768 + kc1); va = GLD(u32x4, Vg + (size_t)tn * 512 + tid);
;         u32x4 pf[4];
;         {
;             f32x16 p0 = {}, p1 = {};
; #pragma unroll
;             for (int s = 0; s < 6; ++s) {
;                 const bf16x8 a0 = *(const LAS bf16x8*)(lds + cur + kfo + s * 32), a1 = *(const LAS bf16x8*)(lds + cur + kfo + 32 * KPITCH + s * 32);
;                 const bf16x8 q = *(const LAS bf16x8*)(ql + s * 1024);
;                 p0 = __builtin_amdgcn_mfma_f32_32x32x16_bf16(a0, q, p0, 0, 0, 0); p1 = __builtin_amdgcn_mfma_f32_32x32x16_bf16(a1, q, p1, 0, 0, 0);
;             }
;             softmax_blk(p0, p1, oa0, oa1, ma, la, pf, t == 0);
;             pv_blk(pf, oa0, oa1, lds + cur + vb);
.Lmla_top:
	ds_read_b64_tr_b16 v[128:129], v158 offset:13312
	ds_read_b64_tr_b16 v[130:131], v158 offset:13824
	ds_read_b64_tr_b16 v[142:143], v158 offset:17408
	ds_read_b64_tr_b16 v[144:145], v158 offset:17920
	ds_read_b64_tr_b16 v[176:177], v158 offset:14336
	ds_read_b64_tr_b16 v[178:179], v158 offset:14848
	ds_read_b64_tr_b16 v[180:181], v158 offset:18432
	ds_read_b64_tr_b16 v[182:183], v158 offset:18944
	s_waitcnt lgkmcnt(4)
	v_mfma_f32_32x32x16_bf16 v[16:31], v[128:131], v[64:67], v[16:31]
	v_mfma_f32_32x32x16_bf16 v[0:15], v[142:145], v[64:67], v[0:15]
	ds_read_b64_tr_b16 v[128:129], v158 offset:15360
	ds_read_b64_tr_b16 v[130:131], v158 offset:15872
	ds_read_b64_tr_b16 v[142:143], v158 offset:19456
	ds_read_b64_tr_b16 v[144:145], v158 offset:19968
	global_load_dwordx4 v[218:221], v171, s[26:27]
	global_load_dwordx4 v[222:225], v184, s[26:27]
	global_load_dwordx4 v[226:229], v146, s[100:101]
	s_add_u32 s26, s26, 0x3000
	s_addc_u32 s27, s27, 0
	s_add_u32 s100, s100, 0x2000
	s_addc_u32 s101, s101, 0
	v_max3_f32 v248, v96, v97, v98
	v_max3_f32 v249, v112, v113, v114
	v_max3_f32 v248, v248, v99, v100
	v_max3_f32 v249, v249, v115, v116
	v_max3_f32 v248, v248, v101, v102
	v_max3_f32 v249, v249, v117, v118
	v_max3_f32 v248, v248, v103, v104
	v_max3_f32 v249, v249, v119, v120
	v_max3_f32 v248, v248, v105, v106
	v_max3_f32 v249, v249, v121, v122
	v_max3_f32 v248, v248, v107, v108
	s_waitcnt lgkmcnt(4)
	v_mfma_f32_32x32x16_bf16 v[16:31], v[176:179], v[68:71], v[16:31]
	v_mfma_f32_32x32x16_bf16 v[0:15], v[180:183], v[68:71], v[0:15]
	ds_read_b64_tr_b16 v[176:177], v158 offset:16384
	ds_read_b64_tr_b16 v[178:179], v158 offset:16896
	ds_read_b64_tr_b16 v[180:181], v158 offset:20480
	ds_read_b64_tr_b16 v[182:183], v158 offset:20992
	v_max3_f32 v249, v249, v123, v124
	v_max3_f32 v248, v248, v109, v110
	v_max3_f32 v249, v249, v125, v126
	v_max3_f32 v248, v248, v111, v127
	v_max_f32_e32 v248, v248, v249
	v_mov_b32_e32 v251, v248
	s_nop 1
	v_permlane32_swap_b32_e32 v248, v251
	v_max_f32_e32 v167, v248, v251
	v_cmp_lt_f32_e32 vcc, s72, v167
	s_waitcnt lgkmcnt(4)
	v_mfma_f32_32x32x16_bf16 v[16:31], v[128:131], v[72:75], v[16:31]
	v_mfma_f32_32x32x16_bf16 v[0:15], v[142:145], v[72:75], v[0:15]
	ds_read_b128 v[128:131], v155 offset:21504
	ds_read_b128 v[142:145], v155 offset:28160
	ds_read_b128 v[162:165], v135 offset:43008
	s_cbranch_vccnz .Lmla_rescBo
.Lmla_rescBo_back:
	v_exp_f32_e32 v96, v96
	v_exp_f32_e32 v97, v97
	v_exp_f32_e32 v98, v98
	v_exp_f32_e32 v99, v99
	v_exp_f32_e32 v100, v100
	v_exp_f32_e32 v101, v101
	v_exp_f32_e32 v102, v102
	v_exp_f32_e32 v103, v103
	v_add_f32_e32 v166, v96, v97
	s_waitcnt lgkmcnt(3)
	v_mfma_f32_32x32x16_bf16 v[16:31], v[176:179], v[76:79], v[16:31]
	v_mfma_f32_32x32x16_bf16 v[0:15], v[180:183], v[76:79], v[0:15]
	ds_read_b128 v[176:179], v155 offset:21536
	ds_read_b128 v[180:183], v155 offset:28192
	ds_read_b128 v[186:189], v135 offset:44032
	v_add_f32_e32 v141, v141, v98
	v_add_f32_e32 v166, v166, v99
	v_cvt_pk_bf16_f32 v96, v96, v97
	v_cvt_pk_bf16_f32 v97, v98, v99
	v_exp_f32_e32 v104, v104
	v_exp_f32_e32 v105, v105
	v_exp_f32_e32 v106, v106
	v_exp_f32_e32 v107, v107
	v_add_f32_e32 v141, v141, v100
	v_add_f32_e32 v166, v166, v101
	s_waitcnt lgkmcnt(3)
	v_mfma_f32_32x32x16_bf16 v[64:79], v[128:131], v[162:165], v[232:247]
	v_mfma_f32_32x32x16_bf16 v[80:95], v[142:145], v[162:165], v[232:247]
	ds_read_b128 v[128:131], v155 offset:21568
	ds_read_b128 v[142:145], v155 offset:28224
	ds_read_b128 v[162:165], v135 offset:45056
	v_add_f32_e32 v141, v141, v102
	v_add_f32_e32 v166, v166, v103
	v_cvt_pk_bf16_f32 v98, v100, v101
	v_cvt_pk_bf16_f32 v99, v102, v103
	v_exp_f32_e32 v108, v108
	v_exp_f32_e32 v109, v109
	v_exp_f32_e32 v110, v110
	v_exp_f32_e32 v111, v111
	v_add_f32_e32 v141, v141, v104
	v_add_f32_e32 v166, v166, v105
	s_waitcnt lgkmcnt(3)
	v_mfma_f32_32x32x16_bf16 v[64:79], v[176:179], v[186:189], v[64:79]
	v_mfma_f32_32x32x16_bf16 v[80:95], v[180:183], v[186:189], v[80:95]
	ds_read_b128 v[176:179], v155 offset:21600
	ds_read_b128 v[180:183], v155 offset:28256
	ds_read_b128 v[186:189], v135 offset:46080
	v_add_f32_e32 v141, v141, v106
	v_add_f32_e32 v166, v166, v107
	v_cvt_pk_bf16_f32 v100, v104, v105
	v_cvt_pk_bf16_f32 v101, v106, v107
	v_exp_f32_e32 v112, v112
	v_exp_f32_e32 v113, v113
	v_exp_f32_e32 v114, v114
	v_exp_f32_e32 v115, v115
	v_add_f32_e32 v141, v141, v108
	v_add_f32_e32 v166, v166, v109
	v_add_f32_e32 v141, v141, v110
	s_waitcnt lgkmcnt(3)
	v_mfma_f32_32x32x16_bf16 v[64:79], v[128:131], v[162:165], v[64:79]
	v_mfma_f32_32x32x16_bf16 v[80:95], v[142:145], v[162:165], v[80:95]
	ds_read_b128 v[128:131], v155 offset:21632
	ds_read_b128 v[142:145], v155 offset:28288
	ds_read_b128 v[162:165], v135 offset:47104
	v_add_f32_e32 v166, v166, v111
	v_cvt_pk_bf16_f32 v102, v108, v109
	v_cvt_pk_bf16_f32 v103, v110, v111
	v_exp_f32_e32 v116, v116
	v_exp_f32_e32 v117, v117
	v_exp_f32_e32 v118, v118
	v_exp_f32_e32 v119, v119
	v_add_f32_e32 v141, v141, v112
	v_add_f32_e32 v166, v166, v113
	v_add_f32_e32 v141, v141, v114
	s_waitcnt lgkmcnt(3)
	v_mfma_f32_32x32x16_bf16 v[64:79], v[176:179], v[186:189], v[64:79]
	v_mfma_f32_32x32x16_bf16 v[80:95], v[180:183], v[186:189], v[80:95]
	ds_read_b128 v[176:179], v155 offset:21664
	ds_read_b128 v[180:183], v155 offset:28320
	ds_read_b128 v[186:189], v135 offset:48128
	v_add_f32_e32 v166, v166, v115
	v_cvt_pk_bf16_f32 v104, v112, v113
	v_cvt_pk_bf16_f32 v105, v114, v115
	v_exp_f32_e32 v120, v120
	v_exp_f32_e32 v121, v121
	v_exp_f32_e32 v122, v122
	v_exp_f32_e32 v123, v123
	v_add_f32_e32 v141, v141, v116
	v_add_f32_e32 v166, v166, v117
	v_add_f32_e32 v141, v141, v118
	s_waitcnt lgkmcnt(3)
; #define LAS __attribute__((address_space(3)))
; __device__ __forceinline__ float swap_max(float m) { auto rr = __builtin_amdgcn_permlane32_swap(__float_as_uint(m), __float_as_uint(m), false, false); return fmaxf(__uint_as_float(rr[0]), __uint_as_float(rr[1])); }
; __device__ __forceinline__ s16x4 vtr(LAS const unsigned char* p) { return __builtin_bit_cast(s16x4, __builtin_amdgcn_ds_read_tr16_b64_v4i16((LAS s16x4*)p)); }
; #define MLA_PACK(P, b) (u32x4){cvt_pk_bf16(P[b], P[b + 1]), cvt_pk_bf16(P[b + 2], P[b + 3]), cvt_pk_bf16(P[b + 4], P[b + 5]), cvt_pk_bf16(P[b + 6], P[b + 7])}
; __device__ __forceinline__ void softmax_blk(f32x16& p0, f32x16& p1, f32x16& o0, f32x16& o1, float& mhat, float& lrun, u32x4 (&pf)[4], bool first) {
;     float r0 = max2_(p0[0], p0[1]), r1 = max2_(p1[0], p1[1]);
; #pragma unroll
;     for (int e = 2; e < 16; ++e) { r0 = max2_(r0, p0[e]); r1 = max2_(r1, p1[e]); }
;     const float rm = swap_max(max2_(r0, r1));
;     if (first || __any(rm - mhat > THR)) {
;         const float mn = first ? rm : fmaxf(rm, mhat); const float f = first ? 0.f : __builtin_amdgcn_exp2f(mhat - mn); mhat = mn; lrun *= f;
; #pragma unroll
;         for (int e = 0; e < 16; ++e) { o0[e] *= f; o1[e] *= f; }
;     }
;     float s0 = 0.f, s1 = 0.f;
; #pragma unroll
;     for (int e = 0; e < 16; ++e) { p0[e] = __builtin_amdgcn_exp2f(p0[e] - mhat); p1[e] = __builtin_amdgcn_exp2f(p1[e] - mhat); s0 += p0[e]; s1 += p1[e]; }
;     lrun += s0 + s1;
;     pf[0] = MLA_PACK(p0, 0); pf[1] = MLA_PACK(p0, 8); pf[2] = MLA_PACK(p1, 0); pf[3] = MLA_PACK(p1, 8);
; }
; __device__ __forceinline__ void pv_blk(const u32x4 (&pf)[4], f32x16& o0, f32x16& o1, LAS const unsigned char* vbase) {
; #pragma unroll
;     for (int ks = 0; ks < 4; ++ks) {
;         const bf16x8 p = __builtin_bit_cast(bf16x8, pf[ks]);
;         { const s16x4 lo = vtr(vbase + ks * 1024), hh = vtr(vbase + ks * 1024 + 512); const bf16x8 vf = {lo[0], lo[1], lo[2], lo[3], hh[0], hh[1], hh[2], hh[3]};
;           o0 = __builtin_amdgcn_mfma_f32_32x32x16_bf16(vf, p, o0, 0, 0, 0); }
;         { const s16x4 lo = vtr(vbase + 4096 + ks * 1024), hh = vtr(vbase + 4096 + ks * 1024 + 512); const bf16x8 vf = {lo[0], lo[1], lo[2], lo[3], hh[0], hh[1], hh[2], hh[3]};
;           o1 = __builtin_amdgcn_mfma_f32_32x32x16_bf16(vf, p, o1, 0, 0, 0); }
;     }
	v_mfma_f32_32x32x16_bf16 v[64:79], v[128:131], v[162:165], v[64:79]
	v_mfma_f32_32x32x16_bf16 v[80:95], v[142:145], v[162:165], v[80:95]
	ds_read_b64_tr_b16 v[128:129], v158 offset:13312
	ds_read_b64_tr_b16 v[130:131], v158 offset:13824
	ds_read_b64_tr_b16 v[142:143], v158 offset:17408
	ds_read_b64_tr_b16 v[144:145], v158 offset:17920
	v_add_f32_e32 v166, v166, v119
	v_cvt_pk_bf16_f32 v106, v116, v117
	v_cvt_pk_bf16_f32 v107, v118, v119
	v_exp_f32_e32 v124, v124
	v_exp_f32_e32 v125, v125
	v_exp_f32_e32 v126, v126
	v_exp_f32_e32 v127, v127
	v_add_f32_e32 v141, v141, v120
	v_add_f32_e32 v166, v166, v121
	v_add_f32_e32 v141, v141, v122
	s_waitcnt lgkmcnt(4)
	v_mfma_f32_32x32x16_bf16 v[64:79], v[176:179], v[186:189], v[64:79]
	v_mfma_f32_32x32x16_bf16 v[80:95], v[180:183], v[186:189], v[80:95]
	ds_read_b64_tr_b16 v[176:177], v158 offset:14336
	ds_read_b64_tr_b16 v[178:179], v158 offset:14848
	ds_read_b64_tr_b16 v[180:181], v158 offset:18432
	ds_read_b64_tr_b16 v[182:183], v158 offset:18944
	v_add_f32_e32 v166, v166, v123
	v_cvt_pk_bf16_f32 v108, v120, v121
	v_cvt_pk_bf16_f32 v109, v122, v123
	v_add_f32_e32 v141, v141, v124
	v_add_f32_e32 v166, v166, v125
	v_add_f32_e32 v141, v141, v126
	v_add_f32_e32 v166, v166, v127
	v_cvt_pk_bf16_f32 v110, v124, v125
	v_cvt_pk_bf16_f32 v111, v126, v127
	v_add_f32_e32 v141, v141, v166
	s_waitcnt lgkmcnt(4)
	v_mfma_f32_32x32x16_bf16 v[48:63], v[128:131], v[96:99], v[48:63]
	v_mfma_f32_32x32x16_bf16 v[32:47], v[142:145], v[96:99], v[32:47]
	ds_read_b64_tr_b16 v[128:129], v158 offset:15360
	ds_read_b64_tr_b16 v[130:131], v158 offset:15872
	ds_read_b64_tr_b16 v[142:143], v158 offset:19456
	ds_read_b64_tr_b16 v[144:145], v158 offset:19968
	v_max3_f32 v248, v64, v65, v66
	v_max3_f32 v249, v80, v81, v82
	v_max3_f32 v248, v248, v67, v68
	v_max3_f32 v249, v249, v83, v84
	v_max3_f32 v248, v248, v69, v70
	v_max3_f32 v249, v249, v85, v86
	v_max3_f32 v248, v248, v71, v72
	v_max3_f32 v249, v249, v87, v88
	v_max3_f32 v248, v248, v73, v74
	v_max3_f32 v249, v249, v89, v90
	v_max3_f32 v248, v248, v75, v76
	s_waitcnt lgkmcnt(4)
	v_mfma_f32_32x32x16_bf16 v[48:63], v[176:179], v[100:103], v[48:63]
	v_mfma_f32_32x32x16_bf16 v[32:47], v[180:183], v[100:103], v[32:47]
	ds_read_b64_tr_b16 v[176:177], v158 offset:16384
	ds_read_b64_tr_b16 v[178:179], v158 offset:16896
	ds_read_b64_tr_b16 v[180:181], v158 offset:20480
	ds_read_b64_tr_b16 v[182:183], v158 offset:20992
	v_max3_f32 v249, v249, v91, v92
	v_max3_f32 v248, v248, v77, v78
	v_max3_f32 v249, v249, v93, v94
	v_max3_f32 v248, v248, v79, v95
	v_max_f32_e32 v248, v248, v249
	v_mov_b32_e32 v251, v248
	s_nop 1
	v_permlane32_swap_b32_e32 v248, v251
	v_max_f32_e32 v167, v248, v251
	v_cmp_lt_f32_e32 vcc, s72, v167
	s_waitcnt lgkmcnt(4)
	v_mfma_f32_32x32x16_bf16 v[48:63], v[128:131], v[104:107], v[48:63]
	v_mfma_f32_32x32x16_bf16 v[32:47], v[142:145], v[104:107], v[32:47]
	ds_read_b128 v[128:131], v155 offset:21504
	ds_read_b128 v[142:145], v155 offset:28160
	ds_read_b128 v[162:165], v135 offset:49152
	s_cbranch_vccnz .Lmla_rescAo
.Lmla_rescAo_back:
	v_exp_f32_e32 v64, v64
	v_exp_f32_e32 v65, v65
	v_exp_f32_e32 v66, v66
	v_exp_f32_e32 v67, v67
	v_exp_f32_e32 v68, v68
	v_exp_f32_e32 v69, v69
	v_exp_f32_e32 v70, v70
	v_exp_f32_e32 v71, v71
	v_add_f32_e32 v166, v64, v65
	s_waitcnt lgkmcnt(3)
	v_mfma_f32_32x32x16_bf16 v[48:63], v[176:179], v[108:111], v[48:63]
	v_mfma_f32_32x32x16_bf16 v[32:47], v[180:183], v[108:111], v[32:47]
	ds_read_b128 v[176:179], v155 offset:21536
	ds_read_b128 v[180:183], v155 offset:28192
	ds_read_b128 v[186:189], v135 offset:50176
	v_add_f32_e32 v140, v140, v66
	v_add_f32_e32 v166, v166, v67
	v_cvt_pk_bf16_f32 v64, v64, v65
	v_cvt_pk_bf16_f32 v65, v66, v67
	v_exp_f32_e32 v72, v72
	v_exp_f32_e32 v73, v73
	v_exp_f32_e32 v74, v74
	v_exp_f32_e32 v75, v75
	v_add_f32_e32 v140, v140, v68
	v_add_f32_e32 v166, v166, v69
	s_waitcnt lgkmcnt(3)
	v_mfma_f32_32x32x16_bf16 v[96:111], v[128:131], v[162:165], v[190:205]
	v_mfma_f32_32x32x16_bf16 v[112:127], v[142:145], v[162:165], v[190:205]
	ds_read_b128 v[128:131], v155 offset:21568
	ds_read_b128 v[142:145], v155 offset:28224
	ds_read_b128 v[162:165], v135 offset:51200
	v_add_f32_e32 v140, v140, v70
	v_add_f32_e32 v166, v166, v71
	v_cvt_pk_bf16_f32 v66, v68, v69
	v_cvt_pk_bf16_f32 v67, v70, v71
	v_exp_f32_e32 v76, v76
	v_exp_f32_e32 v77, v77
	v_exp_f32_e32 v78, v78
	v_exp_f32_e32 v79, v79
	v_add_f32_e32 v140, v140, v72
	v_add_f32_e32 v166, v166, v73
	s_waitcnt lgkmcnt(3)
	v_mfma_f32_32x32x16_bf16 v[96:111], v[176:179], v[186:189], v[96:111]
	v_mfma_f32_32x32x16_bf16 v[112:127], v[180:183], v[186:189], v[112:127]
	ds_read_b128 v[176:179], v155 offset:21600
	ds_read_b128 v[180:183], v155 offset:28256
	ds_read_b128 v[186:189], v135 offset:52224
	v_add_f32_e32 v140, v140, v74
	v_add_f32_e32 v166, v166, v75
	v_cvt_pk_bf16_f32 v68, v72, v73
	v_cvt_pk_bf16_f32 v69, v74, v75
	v_exp_f32_e32 v80, v80
	v_exp_f32_e32 v81, v81
	v_exp_f32_e32 v82, v82
	v_exp_f32_e32 v83, v83
	v_add_f32_e32 v140, v140, v76
	v_add_f32_e32 v166, v166, v77
	v_add_f32_e32 v140, v140, v78
	s_waitcnt lgkmcnt(3)
	v_mfma_f32_32x32x16_bf16 v[96:111], v[128:131], v[162:165], v[96:111]
	v_mfma_f32_32x32x16_bf16 v[112:127], v[142:145], v[162:165], v[112:127]
	ds_read_b128 v[128:131], v155 offset:21632
	ds_read_b128 v[142:145], v155 offset:28288
	ds_read_b128 v[162:165], v135 offset:53248
	v_add_f32_e32 v166, v166, v79
	v_cvt_pk_bf16_f32 v70, v76, v77
	v_cvt_pk_bf16_f32 v71, v78, v79
	v_exp_f32_e32 v84, v84
	v_exp_f32_e32 v85, v85
	v_exp_f32_e32 v86, v86
	v_exp_f32_e32 v87, v87
	v_add_f32_e32 v140, v140, v80
	v_add_f32_e32 v166, v166, v81
	v_add_f32_e32 v140, v140, v82
	s_waitcnt lgkmcnt(3)
; #define LAS __attribute__((address_space(3)))
; __device__ __forceinline__ void attn_unit(const bf16_t* Qh, const bf16_t* Kh, const bf16_t* Vh, bf16_t* Oh  , int S, int qb, LAS unsigned char* lds, int tid) {
;     ...
;     for (int t = 0; t < NT; ++t) {
;         const unsigned cur = (unsigned)(t & 1) * BUF, nxt = BUF - cur;
;         const int tn = t + 1 < NT ? t + 1 : t;
;         ka = GLD(u32x4, Kg + (size_t)tn * 768 + kc0); kb = GLD(u32x4, Kg + (size_t)tn * 768 + kc1); va = GLD(u32x4, Vg + (size_t)tn * 512 + tid);
;     ...
;             for (int s = 0; s < 6; ++s) {
;                 const bf16x8 a0 = *(const LAS bf16x8*)(lds + cur + kfo + s * 32), a1 = *(const LAS bf16x8*)(lds + cur + kfo + 32 * KPITCH + s * 32);
;                 const bf16x8 q = *(const LAS bf16x8*)(ql + (6 + s) * 1024);
;                 p0 = __builtin_amdgcn_mfma_f32_32x32x16_bf16(a0, q, p0, 0, 0, 0); p1 = __builtin_amdgcn_mfma_f32_32x32x16_bf16(a1, q, p1, 0, 0, 0);
;             }
;             softmax_blk(p0, p1, ob0, ob1, mb, lb, pf, t == 0);
;             pv_blk(pf, ob0, ob1, lds + cur + vb);
;         }
;         *(LAS u32x4*)(lds + nxt + kd0) = ka; *(LAS u32x4*)(lds + (has1 ? nxt : 0u) + kd1) = kb; *(LAS u32x4*)(lds + nxt + vd) = va;
;         __syncthreads();
	v_mfma_f32_32x32x16_bf16 v[96:111], v[176:179], v[186:189], v[96:111]
	v_mfma_f32_32x32x16_bf16 v[112:127], v[180:183], v[186:189], v[112:127]
	ds_read_b128 v[176:179], v155 offset:21664
	ds_read_b128 v[180:183], v155 offset:28320
	ds_read_b128 v[186:189], v135 offset:54272
	v_add_f32_e32 v166, v166, v83
	v_cvt_pk_bf16_f32 v72, v80, v81
	v_cvt_pk_bf16_f32 v73, v82, v83
	v_exp_f32_e32 v88, v88
	v_exp_f32_e32 v89, v89
	v_exp_f32_e32 v90, v90
	v_exp_f32_e32 v91, v91
	v_add_f32_e32 v140, v140, v84
	v_add_f32_e32 v166, v166, v85
	v_add_f32_e32 v140, v140, v86
	s_waitcnt vmcnt(0)
	ds_write_b128 v150, v[218:221]
	ds_write_b128 v156, v[222:225]
	ds_write_b128 v157, v[226:229] offset:34816
	s_waitcnt lgkmcnt(6)
	v_mfma_f32_32x32x16_bf16 v[96:111], v[128:131], v[162:165], v[96:111]
	v_mfma_f32_32x32x16_bf16 v[112:127], v[142:145], v[162:165], v[112:127]
	v_add_f32_e32 v166, v166, v87
	v_cvt_pk_bf16_f32 v74, v84, v85
	v_cvt_pk_bf16_f32 v75, v86, v87
	v_exp_f32_e32 v92, v92
	v_exp_f32_e32 v93, v93
	v_exp_f32_e32 v94, v94
	v_exp_f32_e32 v95, v95
	v_add_f32_e32 v140, v140, v88
	v_add_f32_e32 v166, v166, v89
	v_add_f32_e32 v140, v140, v90
	s_waitcnt lgkmcnt(3)
	v_mfma_f32_32x32x16_bf16 v[96:111], v[176:179], v[186:189], v[96:111]
	v_mfma_f32_32x32x16_bf16 v[112:127], v[180:183], v[186:189], v[112:127]
	v_add_f32_e32 v166, v166, v91
	v_cvt_pk_bf16_f32 v76, v88, v89
	v_cvt_pk_bf16_f32 v77, v90, v91
	v_add_f32_e32 v140, v140, v92
	v_add_f32_e32 v166, v166, v93
	v_add_f32_e32 v140, v140, v94
	v_add_f32_e32 v166, v166, v95
	v_cvt_pk_bf16_f32 v78, v92, v93
	v_cvt_pk_bf16_f32 v79, v94, v95
	v_add_f32_e32 v140, v140, v166
	s_waitcnt lgkmcnt(0)
	s_barrier
	s_add_i32 s1, s1, 1
	s_cmp_lg_u32 s1, s18
	s_cbranch_scc0 .Lmla_epi
	ds_read_b64_tr_b16 v[128:129], v158 offset:34816
	ds_read_b64_tr_b16 v[130:131], v158 offset:35328
	ds_read_b64_tr_b16 v[142:143], v158 offset:38912
	ds_read_b64_tr_b16 v[144:145], v158 offset:39424
	ds_read_b64_tr_b16 v[176:177], v158 offset:35840
	ds_read_b64_tr_b16 v[178:179], v158 offset:36352
	ds_read_b64_tr_b16 v[180:181], v158 offset:39936
	ds_read_b64_tr_b16 v[182:183], v158 offset:40448
	s_waitcnt lgkmcnt(4)
	v_mfma_f32_32x32x16_bf16 v[16:31], v[128:131], v[64:67], v[16:31]
	v_mfma_f32_32x32x16_bf16 v[0:15], v[142:145], v[64:67], v[0:15]
	ds_read_b64_tr_b16 v[128:129], v158 offset:36864
	ds_read_b64_tr_b16 v[130:131], v158 offset:37376
	ds_read_b64_tr_b16 v[142:143], v158 offset:40960
	ds_read_b64_tr_b16 v[144:145], v158 offset:41472
	global_load_dwordx4 v[218:221], v171, s[26:27]
	global_load_dwordx4 v[222:225], v184, s[26:27]
	global_load_dwordx4 v[226:229], v146, s[100:101]
	s_add_u32 s26, s26, 0x3000
	s_addc_u32 s27, s27, 0
	s_add_u32 s100, s100, 0x2000
	s_addc_u32 s101, s101, 0
	v_max3_f32 v248, v96, v97, v98
	v_max3_f32 v249, v112, v113, v114
	v_max3_f32 v248, v248, v99, v100
	v_max3_f32 v249, v249, v115, v116
	v_max3_f32 v248, v248, v101, v102
	v_max3_f32 v249, v249, v117, v118
	v_max3_f32 v248, v248, v103, v104
	v_max3_f32 v249, v249, v119, v120
	v_max3_f32 v248, v248, v105, v106
	v_max3_f32 v249, v249, v121, v122
	v_max3_f32 v248, v248, v107, v108
	s_waitcnt lgkmcnt(4)
	v_mfma_f32_32x32x16_bf16 v[16:31], v[176:179], v[68:71], v[16:31]
	v_mfma_f32_32x32x16_bf16 v[0:15], v[180:183], v[68:71], v[0:15]
	ds_read_b64_tr_b16 v[176:177], v158 offset:37888
	ds_read_b64_tr_b16 v[178:179], v158 offset:38400
	ds_read_b64_tr_b16 v[180:181], v158 offset:41984
	ds_read_b64_tr_b16 v[182:183], v158 offset:42496
	v_max3_f32 v249, v249, v123, v124
	v_max3_f32 v248, v248, v109, v110
	v_max3_f32 v249, v249, v125, v126
	v_max3_f32 v248, v248, v111, v127
	v_max_f32_e32 v248, v248, v249
	v_mov_b32_e32 v251, v248
	s_nop 1
	v_permlane32_swap_b32_e32 v248, v251
	v_max_f32_e32 v167, v248, v251
	v_cmp_lt_f32_e32 vcc, s72, v167
	s_waitcnt lgkmcnt(4)
	v_mfma_f32_32x32x16_bf16 v[16:31], v[128:131], v[72:75], v[16:31]
	v_mfma_f32_32x32x16_bf16 v[0:15], v[142:145], v[72:75], v[0:15]
	ds_read_b128 v[128:131], v155
	ds_read_b128 v[142:145], v155 offset:6656
	ds_read_b128 v[162:165], v135 offset:43008
	s_cbranch_vccnz .Lmla_rescBv
.Lmla_rescBv_back:
	v_exp_f32_e32 v96, v96
	v_exp_f32_e32 v97, v97
	v_exp_f32_e32 v98, v98
	v_exp_f32_e32 v99, v99
	v_exp_f32_e32 v100, v100
	v_exp_f32_e32 v101, v101
	v_exp_f32_e32 v102, v102
	v_exp_f32_e32 v103, v103
	v_add_f32_e32 v166, v96, v97
	s_waitcnt lgkmcnt(3)
	v_mfma_f32_32x32x16_bf16 v[16:31], v[176:179], v[76:79], v[16:31]
	v_mfma_f32_32x32x16_bf16 v[0:15], v[180:183], v[76:79], v[0:15]
	ds_read_b128 v[176:179], v155 offset:32
	ds_read_b128 v[180:183], v155 offset:6688
	ds_read_b128 v[186:189], v135 offset:44032
	v_add_f32_e32 v141, v141, v98
	v_add_f32_e32 v166, v166, v99
	v_cvt_pk_bf16_f32 v96, v96, v97
	v_cvt_pk_bf16_f32 v97, v98, v99
	v_exp_f32_e32 v104, v104
	v_exp_f32_e32 v105, v105
	v_exp_f32_e32 v106, v106
	v_exp_f32_e32 v107, v107
	v_add_f32_e32 v141, v141, v100
	v_add_f32_e32 v166, v166, v101
	s_waitcnt lgkmcnt(3)
	v_mfma_f32_32x32x16_bf16 v[64:79], v[128:131], v[162:165], v[232:247]
	v_mfma_f32_32x32x16_bf16 v[80:95], v[142:145], v[162:165], v[232:247]
	ds_read_b128 v[128:131], v155 offset:64
	ds_read_b128 v[142:145], v155 offset:6720
	ds_read_b128 v[162:165], v135 offset:45056
	v_add_f32_e32 v141, v141, v102
	v_add_f32_e32 v166, v166, v103
	v_cvt_pk_bf16_f32 v98, v100, v101
	v_cvt_pk_bf16_f32 v99, v102, v103
	v_exp_f32_e32 v108, v108
	v_exp_f32_e32 v109, v109
	v_exp_f32_e32 v110, v110
	v_exp_f32_e32 v111, v111
	v_add_f32_e32 v141, v141, v104
	v_add_f32_e32 v166, v166, v105
	s_waitcnt lgkmcnt(3)
; #define LAS __attribute__((address_space(3)))
; __device__ __forceinline__ float swap_max(float m) { auto rr = __builtin_amdgcn_permlane32_swap(__float_as_uint(m), __float_as_uint(m), false, false); return fmaxf(__uint_as_float(rr[0]), __uint_as_float(rr[1])); }
; __device__ __forceinline__ s16x4 vtr(LAS const unsigned char* p) { return __builtin_bit_cast(s16x4, __builtin_amdgcn_ds_read_tr16_b64_v4i16((LAS s16x4*)p)); }
; #define MLA_PACK(P, b) (u32x4){cvt_pk_bf16(P[b], P[b + 1]), cvt_pk_bf16(P[b + 2], P[b + 3]), cvt_pk_bf16(P[b + 4], P[b + 5]), cvt_pk_bf16(P[b + 6], P[b + 7])}
; __device__ __forceinline__ void softmax_blk(f32x16& p0, f32x16& p1, f32x16& o0, f32x16& o1, float& mhat, float& lrun, u32x4 (&pf)[4], bool first) {
;     float r0 = max2_(p0[0], p0[1]), r1 = max2_(p1[0], p1[1]);
; #pragma unroll
;     for (int e = 2; e < 16; ++e) { r0 = max2_(r0, p0[e]); r1 = max2_(r1, p1[e]); }
;     const float rm = swap_max(max2_(r0, r1));
;     if (first || __any(rm - mhat > THR)) {
;         const float mn = first ? rm : fmaxf(rm, mhat); const float f = first ? 0.f : __builtin_amdgcn_exp2f(mhat - mn); mhat = mn; lrun *= f;
; #pragma unroll
;         for (int e = 0; e < 16; ++e) { o0[e] *= f; o1[e] *= f; }
;     }
;     float s0 = 0.f, s1 = 0.f;
; #pragma unroll
;     for (int e = 0; e < 16; ++e) { p0[e] = __builtin_amdgcn_exp2f(p0[e] - mhat); p1[e] = __builtin_amdgcn_exp2f(p1[e] - mhat); s0 += p0[e]; s1 += p1[e]; }
;     lrun += s0 + s1;
;     pf[0] = MLA_PACK(p0, 0); pf[1] = MLA_PACK(p0, 8); pf[2] = MLA_PACK(p1, 0); pf[3] = MLA_PACK(p1, 8);
; }
; __device__ __forceinline__ void pv_blk(const u32x4 (&pf)[4], f32x16& o0, f32x16& o1, LAS const unsigned char* vbase) {
; #pragma unroll
;     for (int ks = 0; ks < 4; ++ks) {
;         const bf16x8 p = __builtin_bit_cast(bf16x8, pf[ks]);
;         { const s16x4 lo = vtr(vbase + ks * 1024), hh = vtr(vbase + ks * 1024 + 512); const bf16x8 vf = {lo[0], lo[1], lo[2], lo[3], hh[0], hh[1], hh[2], hh[3]};
;           o0 = __builtin_amdgcn_mfma_f32_32x32x16_bf16(vf, p, o0, 0, 0, 0); }
;         { const s16x4 lo = vtr(vbase + 4096 + ks * 1024), hh = vtr(vbase + 4096 + ks * 1024 + 512); const bf16x8 vf = {lo[0], lo[1], lo[2], lo[3], hh[0], hh[1], hh[2], hh[3]};
;           o1 = __builtin_amdgcn_mfma_f32_32x32x16_bf16(vf, p, o1, 0, 0, 0); }
;     }
	v_mfma_f32_32x32x16_bf16 v[64:79], v[176:179], v[186:189], v[64:79]
	v_mfma_f32_32x32x16_bf16 v[80:95], v[180:183], v[186:189], v[80:95]
	ds_read_b128 v[176:179], v155 offset:96
	ds_read_b128 v[180:183], v155 offset:6752
	ds_read_b128 v[186:189], v135 offset:46080
	v_add_f32_e32 v141, v141, v106
	v_add_f32_e32 v166, v166, v107
	v_cvt_pk_bf16_f32 v100, v104, v105
	v_cvt_pk_bf16_f32 v101, v106, v107
	v_exp_f32_e32 v112, v112
	v_exp_f32_e32 v113, v113
	v_exp_f32_e32 v114, v114
	v_exp_f32_e32 v115, v115
	v_add_f32_e32 v141, v141, v108
	v_add_f32_e32 v166, v166, v109
	v_add_f32_e32 v141, v141, v110
	s_waitcnt lgkmcnt(3)
	v_mfma_f32_32x32x16_bf16 v[64:79], v[128:131], v[162:165], v[64:79]
	v_mfma_f32_32x32x16_bf16 v[80:95], v[142:145], v[162:165], v[80:95]
	ds_read_b128 v[128:131], v155 offset:128
	ds_read_b128 v[142:145], v155 offset:6784
	ds_read_b128 v[162:165], v135 offset:47104
	v_add_f32_e32 v166, v166, v111
	v_cvt_pk_bf16_f32 v102, v108, v109
	v_cvt_pk_bf16_f32 v103, v110, v111
	v_exp_f32_e32 v116, v116
	v_exp_f32_e32 v117, v117
	v_exp_f32_e32 v118, v118
	v_exp_f32_e32 v119, v119
	v_add_f32_e32 v141, v141, v112
	v_add_f32_e32 v166, v166, v113
	v_add_f32_e32 v141, v141, v114
	s_waitcnt lgkmcnt(3)
	v_mfma_f32_32x32x16_bf16 v[64:79], v[176:179], v[186:189], v[64:79]
	v_mfma_f32_32x32x16_bf16 v[80:95], v[180:183], v[186:189], v[80:95]
	ds_read_b128 v[176:179], v155 offset:160
	ds_read_b128 v[180:183], v155 offset:6816
	ds_read_b128 v[186:189], v135 offset:48128
	v_add_f32_e32 v166, v166, v115
	v_cvt_pk_bf16_f32 v104, v112, v113
	v_cvt_pk_bf16_f32 v105, v114, v115
	v_exp_f32_e32 v120, v120
	v_exp_f32_e32 v121, v121
	v_exp_f32_e32 v122, v122
	v_exp_f32_e32 v123, v123
	v_add_f32_e32 v141, v141, v116
	v_add_f32_e32 v166, v166, v117
	v_add_f32_e32 v141, v141, v118
	s_waitcnt lgkmcnt(3)
	v_mfma_f32_32x32x16_bf16 v[64:79], v[128:131], v[162:165], v[64:79]
	v_mfma_f32_32x32x16_bf16 v[80:95], v[142:145], v[162:165], v[80:95]
	ds_read_b64_tr_b16 v[128:129], v158 offset:34816
	ds_read_b64_tr_b16 v[130:131], v158 offset:35328
	ds_read_b64_tr_b16 v[142:143], v158 offset:38912
	ds_read_b64_tr_b16 v[144:145], v158 offset:39424
	v_add_f32_e32 v166, v166, v119
	v_cvt_pk_bf16_f32 v106, v116, v117
	v_cvt_pk_bf16_f32 v107, v118, v119
	v_exp_f32_e32 v124, v124
	v_exp_f32_e32 v125, v125
	v_exp_f32_e32 v126, v126
	v_exp_f32_e32 v127, v127
	v_add_f32_e32 v141, v141, v120
	v_add_f32_e32 v166, v166, v121
	v_add_f32_e32 v141, v141, v122
	s_waitcnt lgkmcnt(4)
	v_mfma_f32_32x32x16_bf16 v[64:79], v[176:179], v[186:189], v[64:79]
	v_mfma_f32_32x32x16_bf16 v[80:95], v[180:183], v[186:189], v[80:95]
	ds_read_b64_tr_b16 v[176:177], v158 offset:35840
	ds_read_b64_tr_b16 v[178:179], v158 offset:36352
	ds_read_b64_tr_b16 v[180:181], v158 offset:39936
	ds_read_b64_tr_b16 v[182:183], v158 offset:40448
	v_add_f32_e32 v166, v166, v123
	v_cvt_pk_bf16_f32 v108, v120, v121
	v_cvt_pk_bf16_f32 v109, v122, v123
	v_add_f32_e32 v141, v141, v124
	v_add_f32_e32 v166, v166, v125
	v_add_f32_e32 v141, v141, v126
	v_add_f32_e32 v166, v166, v127
	v_cvt_pk_bf16_f32 v110, v124, v125
	v_cvt_pk_bf16_f32 v111, v126, v127
	v_add_f32_e32 v141, v141, v166
	s_waitcnt lgkmcnt(4)
	v_mfma_f32_32x32x16_bf16 v[48:63], v[128:131], v[96:99], v[48:63]
	v_mfma_f32_32x32x16_bf16 v[32:47], v[142:145], v[96:99], v[32:47]
	ds_read_b64_tr_b16 v[128:129], v158 offset:36864
	ds_read_b64_tr_b16 v[130:131], v158 offset:37376
	ds_read_b64_tr_b16 v[142:143], v158 offset:40960
	ds_read_b64_tr_b16 v[144:145], v158 offset:41472
	v_max3_f32 v248, v64, v65, v66
	v_max3_f32 v249, v80, v81, v82
	v_max3_f32 v248, v248, v67, v68
	v_max3_f32 v249, v249, v83, v84
	v_max3_f32 v248, v248, v69, v70
	v_max3_f32 v249, v249, v85, v86
	v_max3_f32 v248, v248, v71, v72
	v_max3_f32 v249, v249, v87, v88
	v_max3_f32 v248, v248, v73, v74
	v_max3_f32 v249, v249, v89, v90
	v_max3_f32 v248, v248, v75, v76
	s_waitcnt lgkmcnt(4)
	v_mfma_f32_32x32x16_bf16 v[48:63], v[176:179], v[100:103], v[48:63]
	v_mfma_f32_32x32x16_bf16 v[32:47], v[180:183], v[100:103], v[32:47]
	ds_read_b64_tr_b16 v[176:177], v158 offset:37888
	ds_read_b64_tr_b16 v[178:179], v158 offset:38400
	ds_read_b64_tr_b16 v[180:181], v158 offset:41984
	ds_read_b64_tr_b16 v[182:183], v158 offset:42496
	v_max3_f32 v249, v249, v91, v92
	v_max3_f32 v248, v248, v77, v78
	v_max3_f32 v249, v249, v93, v94
	v_max3_f32 v248, v248, v79, v95
	v_max_f32_e32 v248, v248, v249
	v_mov_b32_e32 v251, v248
	s_nop 1
	v_permlane32_swap_b32_e32 v248, v251
	v_max_f32_e32 v167, v248, v251
	v_cmp_lt_f32_e32 vcc, s72, v167
	s_waitcnt lgkmcnt(4)
	v_mfma_f32_32x32x16_bf16 v[48:63], v[128:131], v[104:107], v[48:63]
	v_mfma_f32_32x32x16_bf16 v[32:47], v[142:145], v[104:107], v[32:47]
	ds_read_b128 v[128:131], v155
	ds_read_b128 v[142:145], v155 offset:6656
	ds_read_b128 v[162:165], v135 offset:49152
	s_cbranch_vccnz .Lmla_rescAe
; #define LAS __attribute__((address_space(3)))
; __device__ __forceinline__ float swap_max(float m) { auto rr = __builtin_amdgcn_permlane32_swap(__float_as_uint(m), __float_as_uint(m), false, false); return fmaxf(__uint_as_float(rr[0]), __uint_as_float(rr[1])); }
; #define MLA_PACK(P, b) (u32x4){cvt_pk_bf16(P[b], P[b + 1]), cvt_pk_bf16(P[b + 2], P[b + 3]), cvt_pk_bf16(P[b + 4], P[b + 5]), cvt_pk_bf16(P[b + 6], P[b + 7])}
; __device__ __forceinline__ float max2_(float a, float b) { return __builtin_amdgcn_fmed3f(a, b, INFINITY); }
; __device__ __forceinline__ void softmax_blk(f32x16& p0, f32x16& p1, f32x16& o0, f32x16& o1, float& mhat, float& lrun, u32x4 (&pf)[4], bool first) {
;     float r0 = max2_(p0[0], p0[1]), r1 = max2_(p1[0], p1[1]);
; #pragma unroll
;     for (int e = 2; e < 16; ++e) { r0 = max2_(r0, p0[e]); r1 = max2_(r1, p1[e]); }
;     const float rm = swap_max(max2_(r0, r1));
;     if (first || __any(rm - mhat > THR)) {
;         const float mn = first ? rm : fmaxf(rm, mhat); const float f = first ? 0.f : __builtin_amdgcn_exp2f(mhat - mn); mhat = mn; lrun *= f;
; #pragma unroll
;         for (int e = 0; e < 16; ++e) { o0[e] *= f; o1[e] *= f; }
;     }
;     float s0 = 0.f, s1 = 0.f;
; #pragma unroll
;     for (int e = 0; e < 16; ++e) { p0[e] = __builtin_amdgcn_exp2f(p0[e] - mhat); p1[e] = __builtin_amdgcn_exp2f(p1[e] - mhat); s0 += p0[e]; s1 += p1[e]; }
;     lrun += s0 + s1;
;     pf[0] = MLA_PACK(p0, 0); pf[1] = MLA_PACK(p0, 8); pf[2] = MLA_PACK(p1, 0); pf[3] = MLA_PACK(p1, 8);
; }
; __device__ __forceinline__ void attn_unit(const bf16_t* Qh, const bf16_t* Kh, const bf16_t* Vh, bf16_t* Oh  , int S, int qb, LAS unsigned char* lds, int tid) {
;     ...
;         *(LAS u32x4*)(lds + nxt + kd0) = ka; *(LAS u32x4*)(lds + (has1 ? nxt : 0u) + kd1) = kb; *(LAS u32x4*)(lds + nxt + vd) = va;
;         __syncthreads();
.Lmla_rescAe_back:
	v_exp_f32_e32 v64, v64
	v_exp_f32_e32 v65, v65
	v_exp_f32_e32 v66, v66
	v_exp_f32_e32 v67, v67
	v_exp_f32_e32 v68, v68
	v_exp_f32_e32 v69, v69
	v_exp_f32_e32 v70, v70
	v_exp_f32_e32 v71, v71
	v_add_f32_e32 v166, v64, v65
	s_waitcnt lgkmcnt(3)
	v_mfma_f32_32x32x16_bf16 v[48:63], v[176:179], v[108:111], v[48:63]
	v_mfma_f32_32x32x16_bf16 v[32:47], v[180:183], v[108:111], v[32:47]
	ds_read_b128 v[176:179], v155 offset:32
	ds_read_b128 v[180:183], v155 offset:6688
	ds_read_b128 v[186:189], v135 offset:50176
	v_add_f32_e32 v140, v140, v66
	v_add_f32_e32 v166, v166, v67
	v_cvt_pk_bf16_f32 v64, v64, v65
	v_cvt_pk_bf16_f32 v65, v66, v67
	v_exp_f32_e32 v72, v72
	v_exp_f32_e32 v73, v73
	v_exp_f32_e32 v74, v74
	v_exp_f32_e32 v75, v75
	v_add_f32_e32 v140, v140, v68
	v_add_f32_e32 v166, v166, v69
	s_waitcnt lgkmcnt(3)
	v_mfma_f32_32x32x16_bf16 v[96:111], v[128:131], v[162:165], v[190:205]
	v_mfma_f32_32x32x16_bf16 v[112:127], v[142:145], v[162:165], v[190:205]
	ds_read_b128 v[128:131], v155 offset:64
	ds_read_b128 v[142:145], v155 offset:6720
	ds_read_b128 v[162:165], v135 offset:51200
	v_add_f32_e32 v140, v140, v70
	v_add_f32_e32 v166, v166, v71
	v_cvt_pk_bf16_f32 v66, v68, v69
	v_cvt_pk_bf16_f32 v67, v70, v71
	v_exp_f32_e32 v76, v76
	v_exp_f32_e32 v77, v77
	v_exp_f32_e32 v78, v78
	v_exp_f32_e32 v79, v79
	v_add_f32_e32 v140, v140, v72
	v_add_f32_e32 v166, v166, v73
	s_waitcnt lgkmcnt(3)
	v_mfma_f32_32x32x16_bf16 v[96:111], v[176:179], v[186:189], v[96:111]
	v_mfma_f32_32x32x16_bf16 v[112:127], v[180:183], v[186:189], v[112:127]
	ds_read_b128 v[176:179], v155 offset:96
	ds_read_b128 v[180:183], v155 offset:6752
	ds_read_b128 v[186:189], v135 offset:52224
	v_add_f32_e32 v140, v140, v74
	v_add_f32_e32 v166, v166, v75
	v_cvt_pk_bf16_f32 v68, v72, v73
	v_cvt_pk_bf16_f32 v69, v74, v75
	v_exp_f32_e32 v80, v80
	v_exp_f32_e32 v81, v81
	v_exp_f32_e32 v82, v82
	v_exp_f32_e32 v83, v83
	v_add_f32_e32 v140, v140, v76
	v_add_f32_e32 v166, v166, v77
	v_add_f32_e32 v140, v140, v78
	s_waitcnt lgkmcnt(3)
	v_mfma_f32_32x32x16_bf16 v[96:111], v[128:131], v[162:165], v[96:111]
	v_mfma_f32_32x32x16_bf16 v[112:127], v[142:145], v[162:165], v[112:127]
	ds_read_b128 v[128:131], v155 offset:128
	ds_read_b128 v[142:145], v155 offset:6784
	ds_read_b128 v[162:165], v135 offset:53248
	v_add_f32_e32 v166, v166, v79
	v_cvt_pk_bf16_f32 v70, v76, v77
	v_cvt_pk_bf16_f32 v71, v78, v79
	v_exp_f32_e32 v84, v84
	v_exp_f32_e32 v85, v85
	v_exp_f32_e32 v86, v86
	v_exp_f32_e32 v87, v87
	v_add_f32_e32 v140, v140, v80
	v_add_f32_e32 v166, v166, v81
	v_add_f32_e32 v140, v140, v82
	s_waitcnt lgkmcnt(3)
	v_mfma_f32_32x32x16_bf16 v[96:111], v[176:179], v[186:189], v[96:111]
	v_mfma_f32_32x32x16_bf16 v[112:127], v[180:183], v[186:189], v[112:127]
	ds_read_b128 v[176:179], v155 offset:160
	ds_read_b128 v[180:183], v155 offset:6816
	ds_read_b128 v[186:189], v135 offset:54272
	v_add_f32_e32 v166, v166, v83
	v_cvt_pk_bf16_f32 v72, v80, v81
	v_cvt_pk_bf16_f32 v73, v82, v83
	v_exp_f32_e32 v88, v88
	v_exp_f32_e32 v89, v89
	v_exp_f32_e32 v90, v90
	v_exp_f32_e32 v91, v91
	v_add_f32_e32 v140, v140, v84
	v_add_f32_e32 v166, v166, v85
	v_add_f32_e32 v140, v140, v86
	s_waitcnt vmcnt(0)
	ds_write_b128 v150, v[218:221] offset:21504
	ds_write_b128 v159, v[222:225]
	ds_write_b128 v157, v[226:229] offset:13312
	s_waitcnt lgkmcnt(6)
	v_mfma_f32_32x32x16_bf16 v[96:111], v[128:131], v[162:165], v[96:111]
	v_mfma_f32_32x32x16_bf16 v[112:127], v[142:145], v[162:165], v[112:127]
	v_add_f32_e32 v166, v166, v87
	v_cvt_pk_bf16_f32 v74, v84, v85
	v_cvt_pk_bf16_f32 v75, v86, v87
	v_exp_f32_e32 v92, v92
	v_exp_f32_e32 v93, v93
	v_exp_f32_e32 v94, v94
	v_exp_f32_e32 v95, v95
	v_add_f32_e32 v140, v140, v88
	v_add_f32_e32 v166, v166, v89
	v_add_f32_e32 v140, v140, v90
	s_waitcnt lgkmcnt(3)
	v_mfma_f32_32x32x16_bf16 v[96:111], v[176:179], v[186:189], v[96:111]
	v_mfma_f32_32x32x16_bf16 v[112:127], v[180:183], v[186:189], v[112:127]
	v_add_f32_e32 v166, v166, v91
	v_cvt_pk_bf16_f32 v76, v88, v89
	v_cvt_pk_bf16_f32 v77, v90, v91
	v_add_f32_e32 v140, v140, v92
	v_add_f32_e32 v166, v166, v93
	v_add_f32_e32 v140, v140, v94
	v_add_f32_e32 v166, v166, v95
	v_cvt_pk_bf16_f32 v78, v92, v93
	v_cvt_pk_bf16_f32 v79, v94, v95
	v_add_f32_e32 v140, v140, v166
	s_waitcnt lgkmcnt(0)
	s_barrier
	s_add_i32 s1, s1, 1
	s_branch .Lmla_top
.Lmla_epi:
	ds_read_b64_tr_b16 v[128:129], v158 offset:34816
	ds_read_b64_tr_b16 v[130:131], v158 offset:35328
	ds_read_b64_tr_b16 v[142:143], v158 offset:38912
	ds_read_b64_tr_b16 v[144:145], v158 offset:39424
	ds_read_b64_tr_b16 v[176:177], v158 offset:35840
	ds_read_b64_tr_b16 v[178:179], v158 offset:36352
	ds_read_b64_tr_b16 v[180:181], v158 offset:39936
	ds_read_b64_tr_b16 v[182:183], v158 offset:40448
	s_waitcnt lgkmcnt(4)
	v_mfma_f32_32x32x16_bf16 v[16:31], v[128:131], v[64:67], v[16:31]
	v_mfma_f32_32x32x16_bf16 v[0:15], v[142:145], v[64:67], v[0:15]
	ds_read_b64_tr_b16 v[128:129], v158 offset:36864
	ds_read_b64_tr_b16 v[130:131], v158 offset:37376
	ds_read_b64_tr_b16 v[142:143], v158 offset:40960
	ds_read_b64_tr_b16 v[144:145], v158 offset:41472
	v_max3_f32 v248, v96, v97, v98
	v_max3_f32 v249, v112, v113, v114
	v_max3_f32 v248, v248, v99, v100
	v_max3_f32 v249, v249, v115, v116
	v_max3_f32 v248, v248, v101, v102
	v_max3_f32 v249, v249, v117, v118
	v_max3_f32 v248, v248, v103, v104
	v_max3_f32 v249, v249, v119, v120
	v_max3_f32 v248, v248, v105, v106
	v_max3_f32 v249, v249, v121, v122
	v_max3_f32 v248, v248, v107, v108
	v_max3_f32 v249, v249, v123, v124
	v_max3_f32 v248, v248, v109, v110
	v_max3_f32 v249, v249, v125, v126
	v_max3_f32 v248, v248, v111, v127
	v_max_f32_e32 v248, v248, v249
	v_mov_b32_e32 v251, v248
	s_nop 1
	v_permlane32_swap_b32_e32 v248, v251
	v_max_f32_e32 v167, v248, v251
	v_cmp_lt_f32_e32 vcc, s72, v167
	s_cbranch_vccnz .Lmla_rescBe
; #define LAS __attribute__((address_space(3)))
; __device__ __forceinline__ s16x4 vtr(LAS const unsigned char* p) { return __builtin_bit_cast(s16x4, __builtin_amdgcn_ds_read_tr16_b64_v4i16((LAS s16x4*)p)); }
; #define MLA_PACK(P, b) (u32x4){cvt_pk_bf16(P[b], P[b + 1]), cvt_pk_bf16(P[b + 2], P[b + 3]), cvt_pk_bf16(P[b + 4], P[b + 5]), cvt_pk_bf16(P[b + 6], P[b + 7])}
; __device__ __forceinline__ void softmax_blk(f32x16& p0, f32x16& p1, f32x16& o0, f32x16& o1, float& mhat, float& lrun, u32x4 (&pf)[4], bool first) {
;     ...
;     for (int e = 0; e < 16; ++e) { p0[e] = __builtin_amdgcn_exp2f(p0[e] - mhat); p1[e] = __builtin_amdgcn_exp2f(p1[e] - mhat); s0 += p0[e]; s1 += p1[e]; }
;     lrun += s0 + s1;
;     pf[0] = MLA_PACK(p0, 0); pf[1] = MLA_PACK(p0, 8); pf[2] = MLA_PACK(p1, 0); pf[3] = MLA_PACK(p1, 8);
; }
; __device__ __forceinline__ void pv_blk(const u32x4 (&pf)[4], f32x16& o0, f32x16& o1, LAS const unsigned char* vbase) {
; #pragma unroll
;     for (int ks = 0; ks < 4; ++ks) {
;         const bf16x8 p = __builtin_bit_cast(bf16x8, pf[ks]);
;         { const s16x4 lo = vtr(vbase + ks * 1024), hh = vtr(vbase + ks * 1024 + 512); const bf16x8 vf = {lo[0], lo[1], lo[2], lo[3], hh[0], hh[1], hh[2], hh[3]};
;           o0 = __builtin_amdgcn_mfma_f32_32x32x16_bf16(vf, p, o0, 0, 0, 0); }
;         { const s16x4 lo = vtr(vbase + 4096 + ks * 1024), hh = vtr(vbase + 4096 + ks * 1024 + 512); const bf16x8 vf = {lo[0], lo[1], lo[2], lo[3], hh[0], hh[1], hh[2], hh[3]};
;           o1 = __builtin_amdgcn_mfma_f32_32x32x16_bf16(vf, p, o1, 0, 0, 0); }
;     }
.Lmla_rescBe_back:
	v_exp_f32_e32 v96, v96
	v_exp_f32_e32 v97, v97
	v_exp_f32_e32 v98, v98
	v_exp_f32_e32 v99, v99
	s_waitcnt lgkmcnt(4)
	v_mfma_f32_32x32x16_bf16 v[16:31], v[176:179], v[68:71], v[16:31]
	v_mfma_f32_32x32x16_bf16 v[0:15], v[180:183], v[68:71], v[0:15]
	ds_read_b64_tr_b16 v[176:177], v158 offset:37888
	ds_read_b64_tr_b16 v[178:179], v158 offset:38400
	ds_read_b64_tr_b16 v[180:181], v158 offset:41984
	ds_read_b64_tr_b16 v[182:183], v158 offset:42496
	v_exp_f32_e32 v100, v100
	v_exp_f32_e32 v101, v101
	v_exp_f32_e32 v102, v102
	v_exp_f32_e32 v103, v103
	v_add_f32_e32 v166, v96, v97
	v_add_f32_e32 v141, v141, v98
	v_add_f32_e32 v166, v166, v99
	v_cvt_pk_bf16_f32 v96, v96, v97
	v_cvt_pk_bf16_f32 v97, v98, v99
	v_exp_f32_e32 v104, v104
	v_exp_f32_e32 v105, v105
	v_exp_f32_e32 v106, v106
	v_exp_f32_e32 v107, v107
	v_add_f32_e32 v141, v141, v100
	v_add_f32_e32 v166, v166, v101
	v_add_f32_e32 v141, v141, v102
	v_add_f32_e32 v166, v166, v103
	v_cvt_pk_bf16_f32 v98, v100, v101
	v_cvt_pk_bf16_f32 v99, v102, v103
	v_exp_f32_e32 v108, v108
	v_exp_f32_e32 v109, v109
	v_exp_f32_e32 v110, v110
	v_exp_f32_e32 v111, v111
	v_add_f32_e32 v141, v141, v104
	v_add_f32_e32 v166, v166, v105
	s_waitcnt lgkmcnt(4)
	v_mfma_f32_32x32x16_bf16 v[16:31], v[128:131], v[72:75], v[16:31]
	v_mfma_f32_32x32x16_bf16 v[0:15], v[142:145], v[72:75], v[0:15]
	ds_read_b64_tr_b16 v[128:129], v158 offset:34816
	ds_read_b64_tr_b16 v[130:131], v158 offset:35328
	ds_read_b64_tr_b16 v[142:143], v158 offset:38912
	ds_read_b64_tr_b16 v[144:145], v158 offset:39424
	v_add_f32_e32 v141, v141, v106
	v_add_f32_e32 v166, v166, v107
	v_cvt_pk_bf16_f32 v100, v104, v105
	v_cvt_pk_bf16_f32 v101, v106, v107
	v_exp_f32_e32 v112, v112
	v_exp_f32_e32 v113, v113
	v_exp_f32_e32 v114, v114
	v_exp_f32_e32 v115, v115
	v_add_f32_e32 v141, v141, v108
	v_add_f32_e32 v166, v166, v109
	v_add_f32_e32 v141, v141, v110
	v_add_f32_e32 v166, v166, v111
	v_cvt_pk_bf16_f32 v102, v108, v109
	v_cvt_pk_bf16_f32 v103, v110, v111
	v_exp_f32_e32 v116, v116
	v_exp_f32_e32 v117, v117
	v_exp_f32_e32 v118, v118
	v_exp_f32_e32 v119, v119
	v_add_f32_e32 v141, v141, v112
	v_add_f32_e32 v166, v166, v113
	v_add_f32_e32 v141, v141, v114
	v_add_f32_e32 v166, v166, v115
	v_cvt_pk_bf16_f32 v104, v112, v113
	v_cvt_pk_bf16_f32 v105, v114, v115
	v_exp_f32_e32 v120, v120
	v_exp_f32_e32 v121, v121
	s_waitcnt lgkmcnt(4)
	v_mfma_f32_32x32x16_bf16 v[16:31], v[176:179], v[76:79], v[16:31]
	v_mfma_f32_32x32x16_bf16 v[0:15], v[180:183], v[76:79], v[0:15]
	ds_read_b64_tr_b16 v[176:177], v158 offset:35840
	ds_read_b64_tr_b16 v[178:179], v158 offset:36352
	ds_read_b64_tr_b16 v[180:181], v158 offset:39936
	ds_read_b64_tr_b16 v[182:183], v158 offset:40448
	v_exp_f32_e32 v122, v122
	v_exp_f32_e32 v123, v123
	v_add_f32_e32 v141, v141, v116
	v_add_f32_e32 v166, v166, v117
	v_add_f32_e32 v141, v141, v118
	v_add_f32_e32 v166, v166, v119
	v_cvt_pk_bf16_f32 v106, v116, v117
	v_cvt_pk_bf16_f32 v107, v118, v119
	v_exp_f32_e32 v124, v124
	v_exp_f32_e32 v125, v125
	v_exp_f32_e32 v126, v126
	v_exp_f32_e32 v127, v127
	v_add_f32_e32 v141, v141, v120
	v_add_f32_e32 v166, v166, v121
	v_add_f32_e32 v141, v141, v122
	v_add_f32_e32 v166, v166, v123
	v_cvt_pk_bf16_f32 v108, v120, v121
	v_cvt_pk_bf16_f32 v109, v122, v123
	v_add_f32_e32 v141, v141, v124
	v_add_f32_e32 v166, v166, v125
	v_add_f32_e32 v141, v141, v126
	v_add_f32_e32 v166, v166, v127
	v_cvt_pk_bf16_f32 v110, v124, v125
	v_cvt_pk_bf16_f32 v111, v126, v127
	v_add_f32_e32 v141, v141, v166
	s_waitcnt lgkmcnt(4)
	v_mfma_f32_32x32x16_bf16 v[48:63], v[128:131], v[96:99], v[48:63]
	v_mfma_f32_32x32x16_bf16 v[32:47], v[142:145], v[96:99], v[32:47]
	ds_read_b64_tr_b16 v[128:129], v158 offset:36864
	ds_read_b64_tr_b16 v[130:131], v158 offset:37376
	ds_read_b64_tr_b16 v[142:143], v158 offset:40960
	ds_read_b64_tr_b16 v[144:145], v158 offset:41472
	s_waitcnt lgkmcnt(4)
	v_mfma_f32_32x32x16_bf16 v[48:63], v[176:179], v[100:103], v[48:63]
	v_mfma_f32_32x32x16_bf16 v[32:47], v[180:183], v[100:103], v[32:47]
	ds_read_b64_tr_b16 v[176:177], v158 offset:37888
	ds_read_b64_tr_b16 v[178:179], v158 offset:38400
	ds_read_b64_tr_b16 v[180:181], v158 offset:41984
	ds_read_b64_tr_b16 v[182:183], v158 offset:42496
	s_waitcnt lgkmcnt(4)
	v_mfma_f32_32x32x16_bf16 v[48:63], v[128:131], v[104:107], v[48:63]
	v_mfma_f32_32x32x16_bf16 v[32:47], v[142:145], v[104:107], v[32:47]
	s_waitcnt lgkmcnt(0)
	v_mfma_f32_32x32x16_bf16 v[48:63], v[176:179], v[108:111], v[48:63]
	v_mfma_f32_32x32x16_bf16 v[32:47], v[180:183], v[108:111], v[32:47]
	s_waitcnt lgkmcnt(0)
	s_barrier
	s_setprio 0
	s_nop 7
	s_nop 3
	s_branch .LBB0_75

; __global__ void __launch_bounds__(512, 2) fwd_kernel(Args args) {
	.amdhsa_kernel _Z10fwd_kernel4Args
		.amdhsa_group_segment_fixed_size 0
		.amdhsa_private_segment_fixed_size 0
		.amdhsa_kernarg_size 448
		.amdhsa_user_sgpr_count 2
		.amdhsa_user_sgpr_dispatch_ptr 0
		.amdhsa_user_sgpr_queue_ptr 0
		.amdhsa_user_sgpr_kernarg_segment_ptr 1
		.amdhsa_user_sgpr_dispatch_id 0
		.amdhsa_user_sgpr_kernarg_preload_length 0
		.amdhsa_user_sgpr_kernarg_preload_offset 0
		.amdhsa_user_sgpr_private_segment_size 0
		.amdhsa_uses_dynamic_stack 0
		.amdhsa_enable_private_segment 0
		.amdhsa_system_sgpr_workgroup_id_x 1
		.amdhsa_system_sgpr_workgroup_id_y 0
		.amdhsa_system_sgpr_workgroup_id_z 0
		.amdhsa_system_sgpr_workgroup_info 0
		.amdhsa_system_vgpr_workitem_id 2
		.amdhsa_next_free_vgpr 256
		.amdhsa_next_free_sgpr 102
		.amdhsa_accum_offset 256
		.amdhsa_reserve_vcc 1
		.amdhsa_float_round_mode_32 0
		.amdhsa_float_round_mode_16_64 0
		.amdhsa_float_denorm_mode_32 3
		.amdhsa_float_denorm_mode_16_64 3
		.amdhsa_dx10_clamp 1
		.amdhsa_ieee_mode 1
		.amdhsa_fp16_overflow 0
		.amdhsa_tg_split 0
		.amdhsa_exception_fp_ieee_invalid_op 0
		.amdhsa_exception_fp_denorm_src 0
		.amdhsa_exception_fp_ieee_div_zero 0
		.amdhsa_exception_fp_ieee_overflow 0
		.amdhsa_exception_fp_ieee_underflow 0
		.amdhsa_exception_fp_ieee_inexact 0
		.amdhsa_exception_int_div_zero 0
	.end_amdhsa_kernel

; __global__ void __launch_bounds__(512, 2) fwd_kernel(Args args) {
amdhsa.kernels:
  - .agpr_count:     0
    .args:
      - .offset:         0
        .size:           192
        .value_kind:     by_value
      - .offset:         192
        .size:           4
        .value_kind:     hidden_block_count_x
      - .offset:         196
        .size:           4
        .value_kind:     hidden_block_count_y
      - .offset:         200
        .size:           4
        .value_kind:     hidden_block_count_z
      - .offset:         204
        .size:           2
        .value_kind:     hidden_group_size_x
      - .offset:         206
        .size:           2
        .value_kind:     hidden_group_size_y
      - .offset:         208
        .size:           2
        .value_kind:     hidden_group_size_z
      - .offset:         210
        .size:           2
        .value_kind:     hidden_remainder_x
      - .offset:         212
        .size:           2
        .value_kind:     hidden_remainder_y
      - .offset:         214
        .size:           2
        .value_kind:     hidden_remainder_z
      - .offset:         232
        .size:           8
        .value_kind:     hidden_global_offset_x
      - .offset:         240
        .size:           8
        .value_kind:     hidden_global_offset_y
      - .offset:         248
        .size:           8
        .value_kind:     hidden_global_offset_z
      - .offset:         256
        .size:           2
        .value_kind:     hidden_grid_dims
      - .offset:         280
        .size:           8
        .value_kind:     hidden_multigrid_sync_arg
      - .offset:         312
        .size:           4
        .value_kind:     hidden_dynamic_lds_size
    .group_segment_fixed_size: 0
    .kernarg_segment_align: 8
    .kernarg_segment_size: 448
    .language:       OpenCL C
    .language_version:
      - 2
      - 0
    .max_flat_workgroup_size: 512
    .name:           _Z10fwd_kernel4Args
    .private_segment_fixed_size: 0
    .sgpr_count:     108
    .sgpr_spill_count: 226
    .symbol:         _Z10fwd_kernel4Args.kd
    .uniform_work_group_size: 1
    .uses_dynamic_stack: false
    .vgpr_count:     256
    .vgpr_spill_count: 0
    .wavefront_size: 64
